# epit
# speedup vs baseline: 1.0448x; 1.0103x over previous
; __device__ __forceinline__ float shfl_idx(float v, int src_lane) { return __builtin_bit_cast(float, __builtin_amdgcn_ds_bpermute(src_lane << 2, __builtin_bit_cast(int, v))); }
;     __device__ __forceinline__ void operator()(f32x4 (&acc)[2][2][4][2], const Unit& u, int wr, int wc, int fr, int fq) const {
;         const int row0 = u.pm * BM + wr * 64 + fr, col0 = u.pn * BM + wc * 32 + 8 * fq, b = (u.pm * BM) >> 13, lane = fr + 16 * fq, tid = (wr * 4 + wc) * 64 + lane;
;         const float* gp = gate + (size_t)b * 6144 + col0;
;         f32x4 gv[2][2];
; #pragma unroll
;         for (int bj = 0; bj < 2; ++bj)
; #pragma unroll
;             for (int n = 0; n < 2; ++n) gv[bj][n] = *(const f32x4*)(gp + bj * HALF + 4 * n);
; #pragma unroll
;         for (int ai = 0; ai < 2; ++ai)
; #pragma unroll
;             for (int m = 0; m < 4; ++m) { const size_t ro = (size_t)(row0 + ai * HALF + m * 16) * 1024 + col0; float ss = 0.f;
; #pragma unroll
;                 for (int bj = 0; bj < 2; ++bj)
; #pragma unroll
;                     for (int n = 0; n < 2; ++n) { const f32x4 xv = *(const f32x4*)(xin + ro + bj * HALF + 4 * n); const f32x4 x = xv + gv[bj][n] * acc[ai][bj][m][n];
;                         *(f32x4*)(out + ro + bj * HALF + 4 * n) = x; acc[ai][bj][m][n] = x; ss += (x.x * x.x + x.y * x.y) + (x.z * x.z + x.w * x.w); }
;                 if (donorm) { ss += shfl_idx(ss, lane ^ 16); ss += shfl_idx(ss, lane ^ 32); if (fq == 0) lp[(ai * HALF + wr * 64 + m * 16 + fr) * 4 + wc] = ss; }
.LBB0_280:
	v_and_b32_e32 v168, 63, v199
	v_bfe_u32 v169, v199, 4, 2
	v_lshlrev_b32_e32 v169, 2, v169
	v_xor_b32_e32 v169, v168, v169
	v_and_b32_e32 v170, 0x1c0, v199
	v_add_u32_e32 v173, 64, v170
	v_and_b32_e32 v173, 0x200, v173
	v_lshl_add_u32 v170, v170, 4, v173
	v_bfe_u32 v173, v199, 8, 1
	v_mul_u32_u24_e32 v173, 0x1400, v173
	v_add_u32_e32 v170, v170, v173
	v_add_u32_e32 v170, 0x20000, v170
	v_lshl_add_u32 v174, v169, 4, v170
	v_lshrrev_b32_e32 v171, 2, v168
	v_and_b32_e32 v172, 3, v168
	v_lshlrev_b32_e32 v173, 2, v172
	v_xor_b32_e32 v171, v171, v173
	v_lshl_or_b32 v171, v172, 4, v171
	v_lshl_add_u32 v175, v171, 4, v170
	ds_write_b128 v174, v[0:3]
	ds_read_b128 v[0:3], v175
	ds_write_b128 v174, v[4:7]
	ds_read_b128 v[4:7], v175
	ds_write_b128 v174, v[8:11]
	ds_read_b128 v[8:11], v175
	ds_write_b128 v174, v[12:15]
	ds_read_b128 v[12:15], v175
	ds_write_b128 v174, v[16:19]
	ds_read_b128 v[16:19], v175
	ds_write_b128 v174, v[20:23]
	ds_read_b128 v[20:23], v175
	ds_write_b128 v174, v[24:27]
	ds_read_b128 v[24:27], v175
	ds_write_b128 v174, v[28:31]
	ds_read_b128 v[28:31], v175
	ds_write_b128 v174, v[32:35]
	ds_read_b128 v[32:35], v175
	ds_write_b128 v174, v[36:39]
	ds_read_b128 v[36:39], v175
	ds_write_b128 v174, v[40:43]
	ds_read_b128 v[40:43], v175
	ds_write_b128 v174, v[44:47]
	ds_read_b128 v[44:47], v175
	ds_write_b128 v174, v[48:51]
	ds_read_b128 v[48:51], v175
	ds_write_b128 v174, v[52:55]
	ds_read_b128 v[52:55], v175
	ds_write_b128 v174, v[56:59]
	ds_read_b128 v[56:59], v175
	ds_write_b128 v174, v[60:63]
	ds_read_b128 v[60:63], v175
	ds_write_b128 v174, v[64:67]
	ds_read_b128 v[64:67], v175
	ds_write_b128 v174, v[68:71]
	ds_read_b128 v[68:71], v175
	ds_write_b128 v174, v[72:75]
	ds_read_b128 v[72:75], v175
	ds_write_b128 v174, v[76:79]
	ds_read_b128 v[76:79], v175
	ds_write_b128 v174, v[80:83]
	ds_read_b128 v[80:83], v175
	ds_write_b128 v174, v[84:87]
	ds_read_b128 v[84:87], v175
	ds_write_b128 v174, v[88:91]
	ds_read_b128 v[88:91], v175
	ds_write_b128 v174, v[92:95]
	ds_read_b128 v[92:95], v175
	ds_write_b128 v174, v[96:99]
	ds_read_b128 v[96:99], v175
	ds_write_b128 v174, v[100:103]
	ds_read_b128 v[100:103], v175
	ds_write_b128 v174, v[104:107]
	ds_read_b128 v[104:107], v175
	ds_write_b128 v174, v[108:111]
	ds_read_b128 v[108:111], v175
	ds_write_b128 v174, v[120:123]
	ds_read_b128 v[120:123], v175
	ds_write_b128 v174, v[128:131]
	ds_read_b128 v[128:131], v175
	ds_write_b128 v174, v[136:139]
	ds_read_b128 v[136:139], v175
	ds_write_b128 v174, v[140:143]
	ds_read_b128 v[140:143], v175
	s_waitcnt lgkmcnt(0)
	s_lshl_b32 s0, s18, 8
	v_mov_b32_e32 v146, v199
	s_add_i32 s8, s0, s31
	s_lshl_b32 s0, s20, 8
	s_or_b32 s0, s0, s33
	v_and_b32_e32 v147, 3, v146
	v_bfe_u32 v214, v146, 2, 4
	v_lshl_or_b32 v186, v147, 3, s0
	s_ashr_i32 s0, s18, 5
	s_mul_hi_i32 s1, s0, 0x1800
	s_mulk_i32 s0, 0x1800
	v_or_b32_e32 v188, s8, v214
	s_lshl_b64 s[22:23], s[0:1], 2
	v_readlane_b32 s0, v254, 58
	v_ashrrev_i32_e32 v189, 31, v188
	s_add_u32 s0, s0, s22
	v_readlane_b32 s1, v254, 59
	v_ashrrev_i32_e32 v187, 31, v186
	v_lshlrev_b64 v[150:151], 12, v[188:189]
	s_addc_u32 s1, s1, s23
	v_lshlrev_b64 v[144:145], 2, v[186:187]
	v_lshl_add_u64 v[150:151], s[84:85], 0, v[150:151]
	v_lshl_add_u64 v[116:117], s[0:1], 0, v[144:145]
	v_lshl_add_u64 v[158:159], v[150:151], 0, v[144:145]
	global_load_dwordx4 v[124:127], v[116:117], off offset:16
	global_load_dwordx4 v[132:135], v[116:117], off
	global_load_dwordx4 v[112:115], v[116:117], off offset:528
	s_nop 0
	global_load_dwordx4 v[116:119], v[116:117], off offset:512
	s_nop 0
	global_load_dwordx4 v[150:153], v[158:159], off offset:16
	global_load_dwordx4 v[154:157], v[158:159], off
	global_load_dwordx4 v[160:163], v[158:159], off offset:528
	global_load_dwordx4 v[164:167], v[158:159], off offset:512
	v_and_b32_e32 v146, 63, v146
	v_lshlrev_b32_e32 v148, 2, v146
	v_xor_b32_e32 v149, 4, v148
	v_xor_b32_e32 v148, 8, v148
	v_cmp_eq_u32_e64 s[8:9], 0, v147
	v_or_b32_e32 v147, s31, v214
	s_andn2_b64 vcc, exec, s[50:51]
	s_waitcnt vmcnt(2)
	v_pk_fma_f32 v[30:31], v[30:31], v[126:127], v[152:153]
	v_pk_fma_f32 v[26:27], v[26:27], v[134:135], v[156:157]
	v_pk_fma_f32 v[24:25], v[24:25], v[132:133], v[154:155]
	v_pk_fma_f32 v[28:29], v[28:29], v[124:125], v[150:151]
	global_store_dwordx4 v[158:159], v[24:27], off
	global_store_dwordx4 v[158:159], v[28:31], off offset:16
	s_waitcnt vmcnt(3)
	v_pk_fma_f32 v[44:45], v[44:45], v[112:113], v[160:161]
	v_cndmask_b32_e64 v150, 0, 1, s[50:51]
	s_waitcnt vmcnt(2)
	v_pk_fma_f32 v[42:43], v[42:43], v[118:119], v[166:167]
	v_pk_fma_f32 v[40:41], v[40:41], v[116:117], v[164:165]
	v_pk_fma_f32 v[46:47], v[46:47], v[114:115], v[162:163]
	v_cmp_ne_u32_e64 s[10:11], 1, v150
	global_store_dwordx4 v[158:159], v[40:43], off offset:512
	global_store_dwordx4 v[158:159], v[44:47], off offset:528
	s_cbranch_vccnz .LBB0_284
	v_mul_f32_e32 v150, v25, v25
	v_mul_f32_e32 v151, v27, v27
	v_fmac_f32_e32 v150, v24, v24
	v_fmac_f32_e32 v151, v26, v26
	v_add_f32_e32 v150, v150, v151
	v_mul_f32_e32 v151, v29, v29
	v_mul_f32_e32 v152, v31, v31
	v_fmac_f32_e32 v151, v28, v28
	v_fmac_f32_e32 v152, v30, v30
	v_add_f32_e32 v151, v151, v152
	v_add_f32_e32 v150, v150, v151
	v_mul_f32_e32 v151, v41, v41
	v_mul_f32_e32 v152, v43, v43
	v_fmac_f32_e32 v151, v40, v40
	v_fmac_f32_e32 v152, v42, v42
	v_add_f32_e32 v151, v151, v152
	v_add_f32_e32 v150, v150, v151
	v_mul_f32_e32 v151, v45, v45
	v_mul_f32_e32 v152, v47, v47
	v_fmac_f32_e32 v151, v44, v44
	v_fmac_f32_e32 v152, v46, v46
	v_add_f32_e32 v151, v151, v152
	v_add_f32_e32 v150, v150, v151
	ds_bpermute_b32 v151, v149, v150
	s_waitcnt lgkmcnt(0)
	v_add_f32_e32 v150, v150, v151
	ds_bpermute_b32 v151, v148, v150
	s_and_saveexec_b64 s[0:1], s[8:9]
	s_cbranch_execz .LBB0_283
	v_lshl_add_u32 v152, v147, 4, s37
	s_waitcnt lgkmcnt(0)
	v_add_f32_e32 v150, v150, v151
	ds_write_b32 v152, v150

; __device__ __forceinline__ float shfl_idx(float v, int src_lane) { return __builtin_bit_cast(float, __builtin_amdgcn_ds_bpermute(src_lane << 2, __builtin_bit_cast(int, v))); }
;     __device__ __forceinline__ void operator()(f32x4 (&acc)[2][2][4][2], const Unit& u, int wr, int wc, int fr, int fq) const {
;     ...
;             for (int m = 0; m < 4; ++m) { const size_t ro = (size_t)(row0 + ai * HALF + m * 16) * 1024 + col0; float ss = 0.f;
; #pragma unroll
;                 for (int bj = 0; bj < 2; ++bj)
; #pragma unroll
;                     for (int n = 0; n < 2; ++n) { const f32x4 xv = *(const f32x4*)(xin + ro + bj * HALF + 4 * n); const f32x4 x = xv + gv[bj][n] * acc[ai][bj][m][n];
;                         *(f32x4*)(out + ro + bj * HALF + 4 * n) = x; acc[ai][bj][m][n] = x; ss += (x.x * x.x + x.y * x.y) + (x.z * x.z + x.w * x.w); }
;                 if (donorm) { ss += shfl_idx(ss, lane ^ 16); ss += shfl_idx(ss, lane ^ 32); if (fq == 0) lp[(ai * HALF + wr * 64 + m * 16 + fr) * 4 + wc] = ss; }
.LBB0_284:
	v_or_b32_e32 v192, 16, v188
	v_ashrrev_i32_e32 v193, 31, v192
	s_waitcnt lgkmcnt(0)
	v_lshlrev_b64 v[150:151], 12, v[192:193]
	v_lshl_add_u64 v[150:151], s[84:85], 0, v[150:151]
	v_lshl_add_u64 v[158:159], v[186:187], 2, v[150:151]
	global_load_dwordx4 v[150:153], v[158:159], off offset:16
	global_load_dwordx4 v[154:157], v[158:159], off
	global_load_dwordx4 v[160:163], v[158:159], off offset:528
	global_load_dwordx4 v[164:167], v[158:159], off offset:512
	s_and_b64 vcc, exec, s[10:11]
	s_waitcnt vmcnt(3)
	v_pk_fma_f32 v[70:71], v[70:71], v[126:127], v[152:153]
	s_waitcnt vmcnt(2)
	v_pk_fma_f32 v[66:67], v[66:67], v[134:135], v[156:157]
	v_pk_fma_f32 v[64:65], v[64:65], v[132:133], v[154:155]
	v_pk_fma_f32 v[68:69], v[68:69], v[124:125], v[150:151]
	global_store_dwordx4 v[158:159], v[64:67], off
	global_store_dwordx4 v[158:159], v[68:71], off offset:16
	s_waitcnt vmcnt(3)
	v_pk_fma_f32 v[74:75], v[74:75], v[114:115], v[162:163]
	s_waitcnt vmcnt(2)
	v_pk_fma_f32 v[78:79], v[78:79], v[118:119], v[166:167]
	v_pk_fma_f32 v[76:77], v[76:77], v[116:117], v[164:165]
	v_pk_fma_f32 v[72:73], v[72:73], v[112:113], v[160:161]
	global_store_dwordx4 v[158:159], v[76:79], off offset:512
	global_store_dwordx4 v[158:159], v[72:75], off offset:528
	s_cbranch_vccnz .LBB0_288
	v_mul_f32_e32 v150, v65, v65
	v_mul_f32_e32 v151, v67, v67
	v_fmac_f32_e32 v150, v64, v64
	v_fmac_f32_e32 v151, v66, v66
	v_add_f32_e32 v150, v150, v151
	v_mul_f32_e32 v151, v69, v69
	v_mul_f32_e32 v152, v71, v71
	v_fmac_f32_e32 v151, v68, v68
	v_fmac_f32_e32 v152, v70, v70
	v_add_f32_e32 v151, v151, v152
	v_add_f32_e32 v150, v150, v151
	v_mul_f32_e32 v151, v77, v77
	v_mul_f32_e32 v152, v79, v79
	v_fmac_f32_e32 v151, v76, v76
	v_fmac_f32_e32 v152, v78, v78
	v_add_f32_e32 v151, v151, v152
	v_add_f32_e32 v150, v150, v151
	v_mul_f32_e32 v151, v73, v73
	v_mul_f32_e32 v152, v75, v75
	v_fmac_f32_e32 v151, v72, v72
	v_fmac_f32_e32 v152, v74, v74
	v_add_f32_e32 v151, v151, v152
	v_add_f32_e32 v150, v150, v151
	ds_bpermute_b32 v151, v149, v150
	s_waitcnt lgkmcnt(0)
	v_add_f32_e32 v150, v150, v151
	ds_bpermute_b32 v151, v148, v150
	s_and_saveexec_b64 s[0:1], s[8:9]
	s_cbranch_execz .LBB0_287
	v_lshl_add_u32 v152, v147, 4, s37
	s_waitcnt lgkmcnt(0)
	v_add_f32_e32 v150, v150, v151
	ds_write_b32 v152, v150 offset:256

; __device__ __forceinline__ float shfl_idx(float v, int src_lane) { return __builtin_bit_cast(float, __builtin_amdgcn_ds_bpermute(src_lane << 2, __builtin_bit_cast(int, v))); }
;     __device__ __forceinline__ void operator()(f32x4 (&acc)[2][2][4][2], const Unit& u, int wr, int wc, int fr, int fq) const {
;     ...
;             for (int m = 0; m < 4; ++m) { const size_t ro = (size_t)(row0 + ai * HALF + m * 16) * 1024 + col0; float ss = 0.f;
; #pragma unroll
;                 for (int bj = 0; bj < 2; ++bj)
; #pragma unroll
;                     for (int n = 0; n < 2; ++n) { const f32x4 xv = *(const f32x4*)(xin + ro + bj * HALF + 4 * n); const f32x4 x = xv + gv[bj][n] * acc[ai][bj][m][n];
;                         *(f32x4*)(out + ro + bj * HALF + 4 * n) = x; acc[ai][bj][m][n] = x; ss += (x.x * x.x + x.y * x.y) + (x.z * x.z + x.w * x.w); }
;                 if (donorm) { ss += shfl_idx(ss, lane ^ 16); ss += shfl_idx(ss, lane ^ 32); if (fq == 0) lp[(ai * HALF + wr * 64 + m * 16 + fr) * 4 + wc] = ss; }
.LBB0_288:
	v_or_b32_e32 v190, 32, v188
	v_ashrrev_i32_e32 v191, 31, v190
	s_waitcnt lgkmcnt(0)
	v_lshlrev_b64 v[150:151], 12, v[190:191]
	v_lshl_add_u64 v[150:151], s[84:85], 0, v[150:151]
	v_lshl_add_u64 v[158:159], v[186:187], 2, v[150:151]
	global_load_dwordx4 v[150:153], v[158:159], off offset:16
	global_load_dwordx4 v[154:157], v[158:159], off
	global_load_dwordx4 v[160:163], v[158:159], off offset:528
	global_load_dwordx4 v[164:167], v[158:159], off offset:512
	s_and_b64 vcc, exec, s[10:11]
	s_waitcnt vmcnt(3)
	v_pk_fma_f32 v[90:91], v[90:91], v[126:127], v[152:153]
	s_waitcnt vmcnt(2)
	v_pk_fma_f32 v[94:95], v[94:95], v[134:135], v[156:157]
	v_pk_fma_f32 v[92:93], v[92:93], v[132:133], v[154:155]
	v_pk_fma_f32 v[88:89], v[88:89], v[124:125], v[150:151]
	global_store_dwordx4 v[158:159], v[92:95], off
	global_store_dwordx4 v[158:159], v[88:91], off offset:16
	s_waitcnt vmcnt(3)
	v_pk_fma_f32 v[98:99], v[98:99], v[114:115], v[162:163]
	s_waitcnt vmcnt(2)
	v_pk_fma_f32 v[102:103], v[102:103], v[118:119], v[166:167]
	v_pk_fma_f32 v[100:101], v[100:101], v[116:117], v[164:165]
	v_pk_fma_f32 v[96:97], v[96:97], v[112:113], v[160:161]
	global_store_dwordx4 v[158:159], v[100:103], off offset:512
	global_store_dwordx4 v[158:159], v[96:99], off offset:528
	s_cbranch_vccnz .LBB0_292
	v_mul_f32_e32 v150, v93, v93
	v_mul_f32_e32 v151, v95, v95
	v_fmac_f32_e32 v150, v92, v92
	v_fmac_f32_e32 v151, v94, v94
	v_add_f32_e32 v150, v150, v151
	v_mul_f32_e32 v151, v89, v89
	v_mul_f32_e32 v152, v91, v91
	v_fmac_f32_e32 v151, v88, v88
	v_fmac_f32_e32 v152, v90, v90
	v_add_f32_e32 v151, v151, v152
	v_add_f32_e32 v150, v150, v151
	v_mul_f32_e32 v151, v101, v101
	v_mul_f32_e32 v152, v103, v103
	v_fmac_f32_e32 v151, v100, v100
	v_fmac_f32_e32 v152, v102, v102
	v_add_f32_e32 v151, v151, v152
	v_add_f32_e32 v150, v150, v151
	v_mul_f32_e32 v151, v97, v97
	v_mul_f32_e32 v152, v99, v99
	v_fmac_f32_e32 v151, v96, v96
	v_fmac_f32_e32 v152, v98, v98
	v_add_f32_e32 v151, v151, v152
	v_add_f32_e32 v150, v150, v151
	ds_bpermute_b32 v151, v149, v150
	s_waitcnt lgkmcnt(0)
	v_add_f32_e32 v150, v150, v151
	ds_bpermute_b32 v151, v148, v150
	s_and_saveexec_b64 s[0:1], s[8:9]
	s_cbranch_execz .LBB0_291
	v_lshl_add_u32 v152, v147, 4, s37
	s_waitcnt lgkmcnt(0)
	v_add_f32_e32 v150, v150, v151
	ds_write_b32 v152, v150 offset:512

; __device__ __forceinline__ float shfl_idx(float v, int src_lane) { return __builtin_bit_cast(float, __builtin_amdgcn_ds_bpermute(src_lane << 2, __builtin_bit_cast(int, v))); }
;     __device__ __forceinline__ void operator()(f32x4 (&acc)[2][2][4][2], const Unit& u, int wr, int wc, int fr, int fq) const {
;     ...
;             for (int m = 0; m < 4; ++m) { const size_t ro = (size_t)(row0 + ai * HALF + m * 16) * 1024 + col0; float ss = 0.f;
; #pragma unroll
;                 for (int bj = 0; bj < 2; ++bj)
; #pragma unroll
;                     for (int n = 0; n < 2; ++n) { const f32x4 xv = *(const f32x4*)(xin + ro + bj * HALF + 4 * n); const f32x4 x = xv + gv[bj][n] * acc[ai][bj][m][n];
;                         *(f32x4*)(out + ro + bj * HALF + 4 * n) = x; acc[ai][bj][m][n] = x; ss += (x.x * x.x + x.y * x.y) + (x.z * x.z + x.w * x.w); }
;                 if (donorm) { ss += shfl_idx(ss, lane ^ 16); ss += shfl_idx(ss, lane ^ 32); if (fq == 0) lp[(ai * HALF + wr * 64 + m * 16 + fr) * 4 + wc] = ss; }
.LBB0_292:
	v_or_b32_e32 v194, 48, v188
	v_ashrrev_i32_e32 v195, 31, v194
	s_waitcnt lgkmcnt(0)
	v_lshlrev_b64 v[150:151], 12, v[194:195]
	v_lshl_add_u64 v[150:151], s[84:85], 0, v[150:151]
	v_lshl_add_u64 v[158:159], v[186:187], 2, v[150:151]
	global_load_dwordx4 v[150:153], v[158:159], off offset:16
	global_load_dwordx4 v[154:157], v[158:159], off
	global_load_dwordx4 v[160:163], v[158:159], off offset:528
	global_load_dwordx4 v[164:167], v[158:159], off offset:512
	s_and_b64 vcc, exec, s[10:11]
	s_waitcnt vmcnt(3)
	v_pk_fma_f32 v[122:123], v[122:123], v[126:127], v[152:153]
	s_waitcnt vmcnt(2)
	v_pk_fma_f32 v[130:131], v[130:131], v[134:135], v[156:157]
	v_pk_fma_f32 v[128:129], v[128:129], v[132:133], v[154:155]
	v_pk_fma_f32 v[120:121], v[120:121], v[124:125], v[150:151]
	global_store_dwordx4 v[158:159], v[128:131], off
	global_store_dwordx4 v[158:159], v[120:123], off offset:16
	s_waitcnt vmcnt(3)
	v_pk_fma_f32 v[138:139], v[138:139], v[114:115], v[162:163]
	s_waitcnt vmcnt(2)
	v_pk_fma_f32 v[142:143], v[142:143], v[118:119], v[166:167]
	v_pk_fma_f32 v[140:141], v[140:141], v[116:117], v[164:165]
	v_pk_fma_f32 v[136:137], v[136:137], v[112:113], v[160:161]
	global_store_dwordx4 v[158:159], v[140:143], off offset:512
	global_store_dwordx4 v[158:159], v[136:139], off offset:528
	s_cbranch_vccnz .LBB0_296
	v_mul_f32_e32 v150, v129, v129
	v_mul_f32_e32 v151, v131, v131
	v_fmac_f32_e32 v150, v128, v128
	v_fmac_f32_e32 v151, v130, v130
	v_add_f32_e32 v150, v150, v151
	v_mul_f32_e32 v151, v121, v121
	v_mul_f32_e32 v152, v123, v123
	v_fmac_f32_e32 v151, v120, v120
	v_fmac_f32_e32 v152, v122, v122
	v_add_f32_e32 v151, v151, v152
	v_add_f32_e32 v150, v150, v151
	v_mul_f32_e32 v151, v141, v141
	v_mul_f32_e32 v152, v143, v143
	v_fmac_f32_e32 v151, v140, v140
	v_fmac_f32_e32 v152, v142, v142
	v_add_f32_e32 v151, v151, v152
	v_add_f32_e32 v150, v150, v151
	v_mul_f32_e32 v151, v137, v137
	v_mul_f32_e32 v152, v139, v139
	v_fmac_f32_e32 v151, v136, v136
	v_fmac_f32_e32 v152, v138, v138
	v_add_f32_e32 v151, v151, v152
	v_add_f32_e32 v150, v150, v151
	ds_bpermute_b32 v151, v149, v150
	s_waitcnt lgkmcnt(0)
	v_add_f32_e32 v150, v150, v151
	ds_bpermute_b32 v151, v148, v150
	s_and_saveexec_b64 s[0:1], s[8:9]
	s_cbranch_execz .LBB0_295
	v_lshl_add_u32 v152, v147, 4, s37
	s_waitcnt lgkmcnt(0)
	v_add_f32_e32 v150, v150, v151
	ds_write_b32 v152, v150 offset:768

; __device__ __forceinline__ float shfl_idx(float v, int src_lane) { return __builtin_bit_cast(float, __builtin_amdgcn_ds_bpermute(src_lane << 2, __builtin_bit_cast(int, v))); }
;     __device__ __forceinline__ void operator()(f32x4 (&acc)[2][2][4][2], const Unit& u, int wr, int wc, int fr, int fq) const {
;     ...
;             for (int m = 0; m < 4; ++m) { const size_t ro = (size_t)(row0 + ai * HALF + m * 16) * 1024 + col0; float ss = 0.f;
; #pragma unroll
;                 for (int bj = 0; bj < 2; ++bj)
; #pragma unroll
;                     for (int n = 0; n < 2; ++n) { const f32x4 xv = *(const f32x4*)(xin + ro + bj * HALF + 4 * n); const f32x4 x = xv + gv[bj][n] * acc[ai][bj][m][n];
;                         *(f32x4*)(out + ro + bj * HALF + 4 * n) = x; acc[ai][bj][m][n] = x; ss += (x.x * x.x + x.y * x.y) + (x.z * x.z + x.w * x.w); }
;                 if (donorm) { ss += shfl_idx(ss, lane ^ 16); ss += shfl_idx(ss, lane ^ 32); if (fq == 0) lp[(ai * HALF + wr * 64 + m * 16 + fr) * 4 + wc] = ss; }
.LBB0_296:
	v_add_u32_e32 v204, 0x80, v188
	v_ashrrev_i32_e32 v205, 31, v204
	s_waitcnt lgkmcnt(0)
	v_lshlrev_b64 v[150:151], 12, v[204:205]
	v_lshl_add_u64 v[150:151], s[84:85], 0, v[150:151]
	v_lshl_add_u64 v[158:159], v[186:187], 2, v[150:151]
	global_load_dwordx4 v[150:153], v[158:159], off offset:16
	global_load_dwordx4 v[154:157], v[158:159], off
	global_load_dwordx4 v[160:163], v[158:159], off offset:528
	global_load_dwordx4 v[164:167], v[158:159], off offset:512
	s_and_b64 vcc, exec, s[10:11]
	s_waitcnt vmcnt(3)
	v_pk_fma_f32 v[106:107], v[106:107], v[126:127], v[152:153]
	s_waitcnt vmcnt(2)
	v_pk_fma_f32 v[110:111], v[110:111], v[134:135], v[156:157]
	v_pk_fma_f32 v[108:109], v[108:109], v[132:133], v[154:155]
	v_pk_fma_f32 v[104:105], v[104:105], v[124:125], v[150:151]
	global_store_dwordx4 v[158:159], v[108:111], off
	global_store_dwordx4 v[158:159], v[104:107], off offset:16
	s_waitcnt vmcnt(3)
	v_pk_fma_f32 v[82:83], v[82:83], v[114:115], v[162:163]
	s_waitcnt vmcnt(2)
	v_pk_fma_f32 v[86:87], v[86:87], v[118:119], v[166:167]
	v_pk_fma_f32 v[84:85], v[84:85], v[116:117], v[164:165]
	v_pk_fma_f32 v[80:81], v[80:81], v[112:113], v[160:161]
	global_store_dwordx4 v[158:159], v[84:87], off offset:512
	global_store_dwordx4 v[158:159], v[80:83], off offset:528
	s_cbranch_vccnz .LBB0_300
	v_mul_f32_e32 v150, v109, v109
	v_mul_f32_e32 v151, v111, v111
	v_fmac_f32_e32 v150, v108, v108
	v_fmac_f32_e32 v151, v110, v110
	v_add_f32_e32 v150, v150, v151
	v_mul_f32_e32 v151, v105, v105
	v_mul_f32_e32 v152, v107, v107
	v_fmac_f32_e32 v151, v104, v104
	v_fmac_f32_e32 v152, v106, v106
	v_add_f32_e32 v151, v151, v152
	v_add_f32_e32 v150, v150, v151
	v_mul_f32_e32 v151, v85, v85
	v_mul_f32_e32 v152, v87, v87
	v_fmac_f32_e32 v151, v84, v84
	v_fmac_f32_e32 v152, v86, v86
	v_add_f32_e32 v151, v151, v152
	v_add_f32_e32 v150, v150, v151
	v_mul_f32_e32 v151, v81, v81
	v_mul_f32_e32 v152, v83, v83
	v_fmac_f32_e32 v151, v80, v80
	v_fmac_f32_e32 v152, v82, v82
	v_add_f32_e32 v151, v151, v152
	v_add_f32_e32 v150, v150, v151
	ds_bpermute_b32 v151, v149, v150
	s_waitcnt lgkmcnt(0)
	v_add_f32_e32 v150, v150, v151
	ds_bpermute_b32 v151, v148, v150
	s_and_saveexec_b64 s[0:1], s[8:9]
	s_cbranch_execz .LBB0_299
	v_lshl_add_u32 v152, v147, 4, s37
	s_waitcnt lgkmcnt(0)
	v_add_f32_e32 v150, v150, v151
	ds_write_b32 v152, v150 offset:2048

; __device__ __forceinline__ float shfl_idx(float v, int src_lane) { return __builtin_bit_cast(float, __builtin_amdgcn_ds_bpermute(src_lane << 2, __builtin_bit_cast(int, v))); }
;     __device__ __forceinline__ void operator()(f32x4 (&acc)[2][2][4][2], const Unit& u, int wr, int wc, int fr, int fq) const {
;     ...
;             for (int m = 0; m < 4; ++m) { const size_t ro = (size_t)(row0 + ai * HALF + m * 16) * 1024 + col0; float ss = 0.f;
; #pragma unroll
;                 for (int bj = 0; bj < 2; ++bj)
; #pragma unroll
;                     for (int n = 0; n < 2; ++n) { const f32x4 xv = *(const f32x4*)(xin + ro + bj * HALF + 4 * n); const f32x4 x = xv + gv[bj][n] * acc[ai][bj][m][n];
;                         *(f32x4*)(out + ro + bj * HALF + 4 * n) = x; acc[ai][bj][m][n] = x; ss += (x.x * x.x + x.y * x.y) + (x.z * x.z + x.w * x.w); }
;                 if (donorm) { ss += shfl_idx(ss, lane ^ 16); ss += shfl_idx(ss, lane ^ 32); if (fq == 0) lp[(ai * HALF + wr * 64 + m * 16 + fr) * 4 + wc] = ss; }
.LBB0_300:
	v_add_u32_e32 v206, 0x90, v188
	v_ashrrev_i32_e32 v207, 31, v206
	s_waitcnt lgkmcnt(0)
	v_lshlrev_b64 v[150:151], 12, v[206:207]
	v_lshl_add_u64 v[150:151], s[84:85], 0, v[150:151]
	v_lshl_add_u64 v[158:159], v[186:187], 2, v[150:151]
	global_load_dwordx4 v[150:153], v[158:159], off offset:16
	global_load_dwordx4 v[154:157], v[158:159], off
	global_load_dwordx4 v[160:163], v[158:159], off offset:528
	global_load_dwordx4 v[164:167], v[158:159], off offset:512
	s_and_b64 vcc, exec, s[10:11]
	s_waitcnt vmcnt(3)
	v_pk_fma_f32 v[58:59], v[58:59], v[126:127], v[152:153]
	s_waitcnt vmcnt(2)
	v_pk_fma_f32 v[62:63], v[62:63], v[134:135], v[156:157]
	v_pk_fma_f32 v[60:61], v[60:61], v[132:133], v[154:155]
	v_pk_fma_f32 v[56:57], v[56:57], v[124:125], v[150:151]
	global_store_dwordx4 v[158:159], v[60:63], off
	global_store_dwordx4 v[158:159], v[56:59], off offset:16
	s_waitcnt vmcnt(3)
	v_pk_fma_f32 v[50:51], v[50:51], v[114:115], v[162:163]
	s_waitcnt vmcnt(2)
	v_pk_fma_f32 v[54:55], v[54:55], v[118:119], v[166:167]
	v_pk_fma_f32 v[52:53], v[52:53], v[116:117], v[164:165]
	v_pk_fma_f32 v[48:49], v[48:49], v[112:113], v[160:161]
	global_store_dwordx4 v[158:159], v[52:55], off offset:512
	global_store_dwordx4 v[158:159], v[48:51], off offset:528
	s_cbranch_vccnz .LBB0_304
	v_mul_f32_e32 v150, v61, v61
	v_mul_f32_e32 v151, v63, v63
	v_fmac_f32_e32 v150, v60, v60
	v_fmac_f32_e32 v151, v62, v62
	v_add_f32_e32 v150, v150, v151
	v_mul_f32_e32 v151, v57, v57
	v_mul_f32_e32 v152, v59, v59
	v_fmac_f32_e32 v151, v56, v56
	v_fmac_f32_e32 v152, v58, v58
	v_add_f32_e32 v151, v151, v152
	v_add_f32_e32 v150, v150, v151
	v_mul_f32_e32 v151, v53, v53
	v_mul_f32_e32 v152, v55, v55
	v_fmac_f32_e32 v151, v52, v52
	v_fmac_f32_e32 v152, v54, v54
	v_add_f32_e32 v151, v151, v152
	v_add_f32_e32 v150, v150, v151
	v_mul_f32_e32 v151, v49, v49
	v_mul_f32_e32 v152, v51, v51
	v_fmac_f32_e32 v151, v48, v48
	v_fmac_f32_e32 v152, v50, v50
	v_add_f32_e32 v151, v151, v152
	v_add_f32_e32 v150, v150, v151
	ds_bpermute_b32 v151, v149, v150
	s_waitcnt lgkmcnt(0)
	v_add_f32_e32 v150, v150, v151
	ds_bpermute_b32 v151, v148, v150
	s_and_saveexec_b64 s[0:1], s[8:9]
	s_cbranch_execz .LBB0_303
	v_lshl_add_u32 v152, v147, 4, s37
	s_waitcnt lgkmcnt(0)
	v_add_f32_e32 v150, v150, v151
	ds_write_b32 v152, v150 offset:2304

; __device__ __forceinline__ float shfl_idx(float v, int src_lane) { return __builtin_bit_cast(float, __builtin_amdgcn_ds_bpermute(src_lane << 2, __builtin_bit_cast(int, v))); }
;     __device__ __forceinline__ void operator()(f32x4 (&acc)[2][2][4][2], const Unit& u, int wr, int wc, int fr, int fq) const {
;     ...
;             for (int m = 0; m < 4; ++m) { const size_t ro = (size_t)(row0 + ai * HALF + m * 16) * 1024 + col0; float ss = 0.f;
; #pragma unroll
;                 for (int bj = 0; bj < 2; ++bj)
; #pragma unroll
;                     for (int n = 0; n < 2; ++n) { const f32x4 xv = *(const f32x4*)(xin + ro + bj * HALF + 4 * n); const f32x4 x = xv + gv[bj][n] * acc[ai][bj][m][n];
;                         *(f32x4*)(out + ro + bj * HALF + 4 * n) = x; acc[ai][bj][m][n] = x; ss += (x.x * x.x + x.y * x.y) + (x.z * x.z + x.w * x.w); }
;                 if (donorm) { ss += shfl_idx(ss, lane ^ 16); ss += shfl_idx(ss, lane ^ 32); if (fq == 0) lp[(ai * HALF + wr * 64 + m * 16 + fr) * 4 + wc] = ss; }
.LBB0_304:
	v_add_u32_e32 v208, 0xa0, v188
	v_ashrrev_i32_e32 v209, 31, v208
	s_waitcnt lgkmcnt(0)
	v_lshlrev_b64 v[150:151], 12, v[208:209]
	v_lshl_add_u64 v[150:151], s[84:85], 0, v[150:151]
	v_lshl_add_u64 v[158:159], v[186:187], 2, v[150:151]
	global_load_dwordx4 v[150:153], v[158:159], off offset:16
	global_load_dwordx4 v[154:157], v[158:159], off
	global_load_dwordx4 v[160:163], v[158:159], off offset:528
	global_load_dwordx4 v[164:167], v[158:159], off offset:512
	s_and_b64 vcc, exec, s[10:11]
	s_waitcnt vmcnt(3)
	v_pk_fma_f32 v[34:35], v[34:35], v[126:127], v[152:153]
	s_waitcnt vmcnt(2)
	v_pk_fma_f32 v[38:39], v[38:39], v[134:135], v[156:157]
	v_pk_fma_f32 v[36:37], v[36:37], v[132:133], v[154:155]
	v_pk_fma_f32 v[32:33], v[32:33], v[124:125], v[150:151]
	global_store_dwordx4 v[158:159], v[36:39], off
	global_store_dwordx4 v[158:159], v[32:35], off offset:16
	s_waitcnt vmcnt(3)
	v_pk_fma_f32 v[18:19], v[18:19], v[114:115], v[162:163]
	s_waitcnt vmcnt(2)
	v_pk_fma_f32 v[22:23], v[22:23], v[118:119], v[166:167]
	v_pk_fma_f32 v[20:21], v[20:21], v[116:117], v[164:165]
	v_pk_fma_f32 v[16:17], v[16:17], v[112:113], v[160:161]
	global_store_dwordx4 v[158:159], v[20:23], off offset:512
	global_store_dwordx4 v[158:159], v[16:19], off offset:528
	s_cbranch_vccnz .LBB0_308
	v_mul_f32_e32 v150, v37, v37
	v_mul_f32_e32 v151, v39, v39
	v_fmac_f32_e32 v150, v36, v36
	v_fmac_f32_e32 v151, v38, v38
	v_add_f32_e32 v150, v150, v151
	v_mul_f32_e32 v151, v33, v33
	v_mul_f32_e32 v152, v35, v35
	v_fmac_f32_e32 v151, v32, v32
	v_fmac_f32_e32 v152, v34, v34
	v_add_f32_e32 v151, v151, v152
	v_add_f32_e32 v150, v150, v151
	v_mul_f32_e32 v151, v21, v21
	v_mul_f32_e32 v152, v23, v23
	v_fmac_f32_e32 v151, v20, v20
	v_fmac_f32_e32 v152, v22, v22
	v_add_f32_e32 v151, v151, v152
	v_add_f32_e32 v150, v150, v151
	v_mul_f32_e32 v151, v17, v17
	v_mul_f32_e32 v152, v19, v19
	v_fmac_f32_e32 v151, v16, v16
	v_fmac_f32_e32 v152, v18, v18
	v_add_f32_e32 v151, v151, v152
	v_add_f32_e32 v150, v150, v151
	ds_bpermute_b32 v151, v149, v150
	s_waitcnt lgkmcnt(0)
	v_add_f32_e32 v150, v150, v151
	ds_bpermute_b32 v151, v148, v150
	s_and_saveexec_b64 s[0:1], s[8:9]
	s_cbranch_execz .LBB0_307
	v_lshl_add_u32 v152, v147, 4, s37
	s_waitcnt lgkmcnt(0)
	v_add_f32_e32 v150, v150, v151
	ds_write_b32 v152, v150 offset:2560

; __device__ __forceinline__ float shfl_idx(float v, int src_lane) { return __builtin_bit_cast(float, __builtin_amdgcn_ds_bpermute(src_lane << 2, __builtin_bit_cast(int, v))); }
;     __device__ __forceinline__ void operator()(f32x4 (&acc)[2][2][4][2], const Unit& u, int wr, int wc, int fr, int fq) const {
;     ...
;             for (int m = 0; m < 4; ++m) { const size_t ro = (size_t)(row0 + ai * HALF + m * 16) * 1024 + col0; float ss = 0.f;
; #pragma unroll
;                 for (int bj = 0; bj < 2; ++bj)
; #pragma unroll
;                     for (int n = 0; n < 2; ++n) { const f32x4 xv = *(const f32x4*)(xin + ro + bj * HALF + 4 * n); const f32x4 x = xv + gv[bj][n] * acc[ai][bj][m][n];
;                         *(f32x4*)(out + ro + bj * HALF + 4 * n) = x; acc[ai][bj][m][n] = x; ss += (x.x * x.x + x.y * x.y) + (x.z * x.z + x.w * x.w); }
;                 if (donorm) { ss += shfl_idx(ss, lane ^ 16); ss += shfl_idx(ss, lane ^ 32); if (fq == 0) lp[(ai * HALF + wr * 64 + m * 16 + fr) * 4 + wc] = ss; }
.LBB0_308:
	v_add_u32_e32 v210, 0xb0, v188
	v_ashrrev_i32_e32 v211, 31, v210
	s_waitcnt lgkmcnt(0)
	v_lshlrev_b64 v[150:151], 12, v[210:211]
	v_lshl_add_u64 v[150:151], s[84:85], 0, v[150:151]
	v_lshl_add_u64 v[158:159], v[186:187], 2, v[150:151]
	global_load_dwordx4 v[150:153], v[158:159], off offset:16
	global_load_dwordx4 v[154:157], v[158:159], off
	global_load_dwordx4 v[160:163], v[158:159], off offset:528
	global_load_dwordx4 v[164:167], v[158:159], off offset:512
	s_and_b64 vcc, exec, s[10:11]
	s_waitcnt vmcnt(3)
	v_pk_fma_f32 v[10:11], v[10:11], v[126:127], v[152:153]
	s_waitcnt vmcnt(2)
	v_pk_fma_f32 v[14:15], v[14:15], v[134:135], v[156:157]
	v_pk_fma_f32 v[12:13], v[12:13], v[132:133], v[154:155]
	v_pk_fma_f32 v[8:9], v[8:9], v[124:125], v[150:151]
	global_store_dwordx4 v[158:159], v[12:15], off
	global_store_dwordx4 v[158:159], v[8:11], off offset:16
	s_waitcnt vmcnt(3)
	v_pk_fma_f32 v[2:3], v[2:3], v[114:115], v[162:163]
	s_waitcnt vmcnt(2)
	v_pk_fma_f32 v[6:7], v[6:7], v[118:119], v[166:167]
	v_pk_fma_f32 v[4:5], v[4:5], v[116:117], v[164:165]
	v_pk_fma_f32 v[0:1], v[0:1], v[112:113], v[160:161]
	global_store_dwordx4 v[158:159], v[4:7], off offset:512
	global_store_dwordx4 v[158:159], v[0:3], off offset:528
	s_cbranch_vccnz .LBB0_322
	v_mul_f32_e32 v112, v13, v13
	v_mul_f32_e32 v113, v15, v15
	v_fmac_f32_e32 v112, v12, v12
	v_fmac_f32_e32 v113, v14, v14
	v_add_f32_e32 v112, v112, v113
	v_mul_f32_e32 v113, v9, v9
	v_mul_f32_e32 v114, v11, v11
	v_fmac_f32_e32 v113, v8, v8
	v_fmac_f32_e32 v114, v10, v10
	v_add_f32_e32 v113, v113, v114
	v_add_f32_e32 v112, v112, v113
	v_mul_f32_e32 v113, v5, v5
	v_mul_f32_e32 v114, v7, v7
	v_fmac_f32_e32 v113, v4, v4
	v_fmac_f32_e32 v114, v6, v6
	v_add_f32_e32 v113, v113, v114
	v_add_f32_e32 v112, v112, v113
	v_mul_f32_e32 v113, v1, v1
	v_mul_f32_e32 v114, v3, v3
	v_fmac_f32_e32 v113, v0, v0
	v_fmac_f32_e32 v114, v2, v2
	v_add_f32_e32 v113, v113, v114
	v_add_f32_e32 v112, v112, v113
	ds_bpermute_b32 v113, v149, v112
	s_waitcnt lgkmcnt(0)
	v_add_f32_e32 v112, v112, v113
	ds_bpermute_b32 v113, v148, v112
	s_and_saveexec_b64 s[0:1], s[8:9]
	s_cbranch_execz .LBB0_311
	v_lshl_add_u32 v114, v147, 4, s37
	s_waitcnt lgkmcnt(0)
	v_add_f32_e32 v112, v112, v113
	ds_write_b32 v114, v112 offset:2816

; __global__ void __launch_bounds__(512, 2) fwd_megakernel(Params kp_) {
;     ...
;                         PHASE_IDS;
;                         float* kc = (float*)lds; float* vc = kc + 8192; float* qc = vc + 8192;
;                         bf16* qbf = (bf16*)(lds + 98304); bf16* kbf = qbf + 64 * 136;
;                         float* gc = (float*)(lds + 133120); float* bet = gc + 64;
;                         const float* convw = p.hyb_conv + (size_t)li * 4 * 1536;
;                         for (int item = bid; item < 2048; item += G) {
;                             const int n = item & 127, bh = item >> 7, h = bh & 3, b = bh >> 2;
;                             const int row0 = b * SEQ + n * 64, tpos0 = n * 64;
;                             if (tid < 384) {
;                                 const int cg = tid % 48, rg = tid / 48, part = cg >> 4, d = (cg & 15) * 8, ch = part * 512 + h * 128 + d;
;                                 u32x4 raw[11];
; #pragma unroll
;                                 for (int rr = 0; rr < 11; ++rr) { const int i = rg * 8 - 3 + rr;
;                                     raw[rr] = (tpos0 + i >= 0) ? *(const u32x4*)(proj + (size_t)(row0 + i) * HYBN + ch) : (u32x4){0u, 0u, 0u, 0u}; }
;                                 f32x4 wa[4], wb[4];
; #pragma unroll
;                                 for (int j = 0; j < 4; ++j) { wa[j] = *(const f32x4*)(convw + j * 1536 + ch); wb[j] = *(const f32x4*)(convw + j * 1536 + ch + 4); }
;     ...
;                                 const int d = tid & 127, ih = (tid >> 7) & 1; const float gl = gc[63];
;                                 bf16* kd = KDT + (size_t)item * 8192 + d * 64 + ih * 32;
.LBB0_668:
	s_and_b64 vcc, exec, s[0:1]
	s_cbranch_vccz .LBB0_1005
	v_readlane_b32 s0, v253, 16
	v_mov_b32_e32 v0, v199
	v_readlane_b32 s1, v253, 17
	s_andn2_b64 vcc, exec, s[0:1]
	v_readfirstlane_b32 s3, v0
	s_cbranch_vccnz .LBB0_791
	s_movk_i32 s1, 0x180
	v_cmp_gt_i32_e64 s[36:37], s1, v0
	s_mov_b32 s1, 0x2aaaaaab
	v_mul_hi_i32 v1, v0, s1
	v_lshrrev_b32_e32 v2, 31, v1
	v_ashrrev_i32_e32 v1, 3, v1
	v_add_u32_e32 v1, v1, v2
	v_mul_lo_u32 v2, v1, 48
	s_ashr_i32 s0, s3, 6
	v_sub_u32_e32 v2, v0, v2
	s_add_i32 s1, 0, 0x8000
	s_add_i32 s4, 0, 0x10000
	v_lshlrev_b32_e32 v3, 3, v2
	s_cmp_eq_u32 s0, 7
	v_and_b32_e32 v6, 0x78, v3
	v_mov_b32_e32 v3, s1
	s_cselect_b64 s[38:39], -1, 0
	s_lshl_b32 s30, s0, 10
	s_lshl_b32 s1, s0, 3
	v_and_b32_e32 v98, 63, v0
	v_readlane_b32 s6, v253, 12
	s_cmpk_gt_u32 s3, 0xff
	v_lshlrev_b32_e32 v196, 1, v98
	v_readlane_b32 s7, v253, 13
	s_cselect_b64 s[34:35], -1, 0
	s_add_i32 s2, 0, 0x18000
	s_waitcnt vmcnt(1)
	v_lshl_add_u64 v[76:77], s[6:7], 0, v[196:197]
	s_cmpk_lt_u32 s3, 0x100
	v_readlane_b32 s6, v254, 29
	s_cselect_b32 s3, s6, s2
	s_lshl_b32 s5, s0, 4
	v_and_b32_e32 v99, 15, v0
	s_and_b32 s5, s5, 48
	v_cmp_eq_u32_e64 s[8:9], 0, v98
	v_ashrrev_i32_e32 v5, 4, v2
	v_lshlrev_b32_e32 v100, 3, v1
	v_lshlrev_b32_e32 v8, 12, v1
	v_or_b32_e32 v1, s5, v99
	v_writelane_b32 v255, s8, 30
	v_cmp_eq_u32_e32 vcc, 1, v5
	v_mul_u32_u24_e32 v1, 0x110, v1
	v_and_b32_e32 v13, 48, v0
	v_writelane_b32 v255, s9, 31
	v_cmp_gt_u32_e64 s[8:9], 2, v98
	v_cndmask_b32_e64 v3, v3, 0, vcc
	v_mov_b32_e32 v7, s4
	v_cmp_gt_u32_e32 vcc, 16, v2
	v_add3_u32 v102, s3, v1, v13
	s_movk_i32 s3, 0xff
	v_and_b32_e32 v1, 0x7f, v0
	v_lshrrev_b32_e32 v14, 2, v0
	v_writelane_b32 v255, s8, 32
	v_cndmask_b32_e32 v2, v3, v7, vcc
	v_cmp_lt_i32_e64 s[42:43], s3, v0
	v_bfe_u32 v196, v1, 4, 3
	v_lshlrev_b32_e32 v196, 7, v196
	v_and_or_b32 v196, v1, 15, v196
	v_lshlrev_b32_e32 v196, 4, v196
	v_and_b32_e32 v14, 32, v14
	s_movk_i32 s3, 0x7f
	v_writelane_b32 v255, s9, 33
	v_cmp_gt_u32_e64 s[8:9], 4, v98
	v_lshl_add_u32 v7, v6, 2, v2
	v_lshl_add_u64 v[2:3], s[92:93], 0, v[196:197]
	v_lshlrev_b32_e32 v196, 5, v14
	v_lshl_add_u32 v15, v1, 1, s6
	v_cmp_lt_i32_e64 s[10:11], s3, v0
	v_lshl_add_u32 v1, v0, 2, 0
	s_movk_i32 s3, 0x80
	v_writelane_b32 v255, s8, 34
	v_lshl_add_u64 v[78:79], v[2:3], 0, v[196:197]
	v_add_u32_e32 v2, 0x8000, v1
	v_add_u32_e32 v1, 0xfffffe00, v1
	v_cmp_gt_i32_e64 s[12:13], s3, v0
	v_writelane_b32 v255, s9, 35
	v_cmp_gt_u32_e64 s[8:9], 8, v98
	v_mov_b32_e32 v3, 0x1a800000
	v_mov_b32_e32 v16, 0x18800000
	v_cndmask_b32_e64 v104, v1, v2, s[12:13]
	v_add_u32_e32 v1, 0xffffff80, v0
	v_writelane_b32 v255, s8, 36
	v_bfe_u32 v4, v0, 4, 2
	v_cmp_eq_u32_e64 s[40:41], 0, v0
	v_cndmask_b32_e64 v196, v3, v16, s[12:13]
	v_cndmask_b32_e64 v0, v1, v0, s[12:13]
	v_writelane_b32 v255, s9, 37
	v_cmp_gt_u32_e64 s[8:9], 16, v98
	v_or_b32_e32 v9, s30, v98
	v_lshl_add_u64 v[2:3], s[86:87], 0, v[196:197]
	v_ashrrev_i32_e32 v1, 31, v0
	v_writelane_b32 v255, s8, 38
	s_lshl_b32 s3, s0, 5
	v_readlane_b32 s7, v254, 30
	v_or_b32_e32 v10, 64, v98
	v_lshl_add_u64 v[80:81], v[0:1], 1, v[2:3]
	v_writelane_b32 v255, s9, 39
	v_cmp_gt_u32_e64 s[8:9], 32, v98
	v_lshlrev_b32_e32 v0, 2, v9
	s_add_i32 s44, s7, s3
	s_mul_i32 s3, s0, 0x440
	v_lshlrev_b32_e32 v11, 2, v98
	v_writelane_b32 v255, s8, 40
	v_add_u32_e32 v120, s4, v0
	v_add_u32_e32 v122, 0, v0
	v_or_b32_e32 v0, s3, v98
	v_add_lshl_u32 v1, v10, s3, 1
	s_or_b32 s3, s1, 1
	v_add_u32_e32 v12, 0, v11
	v_writelane_b32 v255, s9, 41
	s_lshl_b32 s4, s3, 2
	s_lshl_b32 s8, s3, 7
	s_add_i32 s45, s7, s4
	s_mul_i32 s4, s3, 0x88
	v_lshl_add_u32 v152, s3, 9, v12
	s_ashr_i32 s9, s8, 31
	s_or_b32 s3, s1, 2
	v_lshl_or_b32 v103, v4, 2, s5
	v_writelane_b32 v255, s8, 42
	s_lshl_b32 s5, s3, 2
	v_lshlrev_b32_e32 v0, 1, v0
	v_writelane_b32 v255, s9, 43
	s_add_i32 s5, s7, s5
	s_lshl_b32 s8, s3, 7
	v_add_u32_e32 v143, s2, v0
	v_add_u32_e32 v144, s2, v1
	v_add_u32_e32 v145, s6, v0
	v_add_u32_e32 v146, s6, v1
	v_add_lshl_u32 v0, s4, v98, 1
	v_add_lshl_u32 v1, v10, s4, 1
	v_writelane_b32 v255, s5, 44
	s_add_i32 s5, s4, 0x88
	v_lshl_add_u32 v157, s3, 9, v12
	s_ashr_i32 s9, s8, 31
	s_or_b32 s3, s1, 3
	v_add_u32_e32 v148, s2, v0
	v_add_u32_e32 v149, s2, v1
	v_add_u32_e32 v150, s6, v0
	v_add_u32_e32 v151, s6, v1
	v_add_lshl_u32 v0, s5, v98, 1
	v_add_lshl_u32 v1, v10, s5, 1
	v_writelane_b32 v255, s8, 45
	s_lshl_b32 s5, s3, 2
	s_add_i32 s5, s7, s5
	v_writelane_b32 v255, s9, 46
	s_lshl_b32 s8, s3, 7
	v_writelane_b32 v255, s5, 47
	s_add_i32 s5, s4, 0x110
	v_lshl_add_u32 v162, s3, 9, v12
	s_ashr_i32 s9, s8, 31
	s_or_b32 s3, s1, 4
	v_add_u32_e32 v153, s2, v0
	v_add_u32_e32 v154, s2, v1
	v_add_u32_e32 v155, s6, v0
; __device__ __forceinline__ unsigned f2bf(float f) { return pk2(f, 0.f) & 0xffffu; }
; #define MFMA16(a, b, c) __builtin_amdgcn_mfma_f32_16x16x32_bf16((a), (b), (c), 0, 0, 0)
; __global__ void __launch_bounds__(512, 2) fwd_megakernel(Params kp_) {
;     ...
;                                 for (int q4 = 0; q4 < 4; ++q4) { const int idx = wave * 4 + q4, kind = idx >> 4, ti = (idx >> 2) & 3, tj = idx & 3;
;                                     const bf16* Ab = (kind == 0 ? kbf : qbf) + (ti * 16 + r16) * 136 + g4 * 8; const bf16* Bb = kbf + (tj * 16 + r16) * 136 + g4 * 8;
;                                     f32x4 acc = {0.f, 0.f, 0.f, 0.f};
; #pragma unroll
;                                     for (int k0 = 0; k0 < 128; k0 += 32) acc = MFMA16(*(const bf16x8*)(Ab + k0), *(const bf16x8*)(Bb + k0), acc);
;                                     const int jj = tj * 16 + r16; const float gj = gc[jj];
; #pragma unroll
;                                     for (int j = 0; j < 4; ++j) { const int i = ti * 16 + g4 * 4 + j; const float dec = __expf(fminf(gc[i] - gj, 0.f));
;                                         if (kind == 0) Ls[i * 64 + jj] = (i > jj) ? acc[j] * bet[i] * dec : 0.f;
;                                         else AAbuf[(size_t)item * 4096 + i * 64 + jj] = (bf16)f2bf((i >= jj) ? acc[j] * dec : 0.f); }
	v_add_u32_e32 v156, s6, v1
	v_add_lshl_u32 v0, s5, v98, 1
	v_add_lshl_u32 v1, v10, s5, 1
	v_writelane_b32 v255, s8, 48
	s_lshl_b32 s5, s3, 2
	s_add_i32 s5, s7, s5
	v_writelane_b32 v255, s9, 49
	s_lshl_b32 s8, s3, 7
	v_writelane_b32 v255, s5, 50
	s_add_i32 s5, s4, 0x198
	v_lshl_add_u32 v167, s3, 9, v12
	s_ashr_i32 s9, s8, 31
	s_or_b32 s3, s1, 5
	v_add_u32_e32 v158, s2, v0
	v_add_u32_e32 v159, s2, v1
	v_add_u32_e32 v160, s6, v0
	v_add_u32_e32 v161, s6, v1
	v_add_lshl_u32 v0, s5, v98, 1
	v_add_lshl_u32 v1, v10, s5, 1
	v_writelane_b32 v255, s8, 51
	s_lshl_b32 s5, s3, 2
	s_add_i32 s5, s7, s5
	v_writelane_b32 v255, s9, 52
	s_lshl_b32 s8, s3, 7
	v_writelane_b32 v255, s5, 53
	s_add_i32 s5, s4, 0x220
	v_lshl_add_u32 v172, s3, 9, v12
	s_ashr_i32 s9, s8, 31
	s_or_b32 s3, s1, 6
	v_add_u32_e32 v163, s2, v0
	v_add_u32_e32 v164, s2, v1
	v_add_u32_e32 v165, s6, v0
	v_add_u32_e32 v166, s6, v1
	v_add_lshl_u32 v0, s5, v98, 1
	v_add_lshl_u32 v1, v10, s5, 1
	v_writelane_b32 v255, s8, 54
	s_lshl_b32 s5, s3, 2
	s_add_i32 s5, s7, s5
	v_writelane_b32 v255, s9, 55
	v_writelane_b32 v255, s5, 56
	s_add_i32 s5, s4, 0x2a8
	v_add_u32_e32 v168, s2, v0
	v_add_u32_e32 v170, s6, v0
	v_add_lshl_u32 v0, s5, v98, 1
	s_addk_i32 s4, 0x330
	v_add_u32_e32 v173, s2, v0
	v_add_u32_e32 v175, s6, v0
	s_or_b32 s1, s1, 7
	v_add_lshl_u32 v0, s4, v98, 1
	s_lshl_b32 s14, s3, 7
	v_lshl_add_u32 v177, s3, 9, v12
	s_lshl_b32 s3, s1, 2
	v_add_u32_e32 v178, s2, v0
	v_add_u32_e32 v180, s6, v0
	s_lshl_b32 s16, s1, 7
	v_lshl_add_u32 v182, s1, 9, v12
	v_lshlrev_b32_e32 v0, 2, v103
	v_readlane_b32 s1, v254, 31
	v_or_b32_e32 v185, 1, v103
	v_add_u32_e32 v183, s7, v0
	v_add_u32_e32 v184, s1, v0
	v_lshlrev_b32_e32 v0, 2, v185
	v_or_b32_e32 v188, 2, v103
	v_add_u32_e32 v169, s2, v1
	v_add_u32_e32 v171, s6, v1
	v_add_lshl_u32 v1, v10, s5, 1
	v_add_u32_e32 v186, s7, v0
	v_add_u32_e32 v187, s1, v0
	v_lshlrev_b32_e32 v0, 2, v188
	v_or_b32_e32 v191, 3, v103
	v_lshl_add_u32 v147, s0, 12, v12
	v_add_u32_e32 v174, s2, v1
	v_add_u32_e32 v176, s6, v1
	v_add_lshl_u32 v1, v10, s4, 1
	v_add_u32_e32 v189, s7, v0
	v_add_u32_e32 v190, s1, v0
	v_lshlrev_b32_e32 v0, 2, v191
	s_and_b32 s0, s0, 3
	v_add_u32_e32 v179, s2, v1
	v_add_u32_e32 v181, s6, v1
	v_add_u32_e32 v193, s1, v0
	s_lshl_b32 s1, s0, 12
	v_lshlrev_b32_e32 v1, 10, v4
	v_lshlrev_b32_e32 v211, 2, v99
	v_or3_b32 v212, s1, v1, v211
	s_movk_i32 s1, 0x110
	v_lshlrev_b32_e32 v1, 6, v4
	s_lshl_b32 s0, s0, 11
	v_bfe_u32 v196, v99, 3, 1
	v_and_b32_e32 v2, 7, v99
	v_lshlrev_b32_e32 v2, 1, v2
	v_lshl_or_b32 v2, v196, 8, v2
	v_mad_u32_u24 v213, v99, s1, v13
	v_or3_b32 v196, s0, v1, v2
	v_readlane_b32 s0, v254, 20
	v_readlane_b32 s1, v254, 21
	s_add_i32 s3, s7, s3
	v_add_u32_e32 v192, s7, v0
	v_lshl_add_u64 v[82:83], s[0:1], 0, v[196:197]
	v_readlane_b32 s0, v254, 22
	v_mul_u32_u24_e32 v0, 0x110, v14
	v_lshl_add_u32 v194, v14, 2, s7
	v_and_b32_e32 v196, 12, v103
	v_lshl_or_b32 v2, v196, 4, v2
	v_and_b32_e32 v196, 0x30, v103
	v_lshl_or_b32 v196, v196, 7, v2
	v_readlane_b32 s1, v254, 23
	v_add_u32_e32 v101, -3, v100
	v_add_u32_e32 v105, -2, v100
	v_add_u32_e32 v106, -1, v100
	v_or_b32_e32 v107, 1, v100
	v_or_b32_e32 v108, 2, v100
	v_or_b32_e32 v109, 3, v100
	v_or_b32_e32 v110, 4, v100
	v_or_b32_e32 v111, 5, v100
	v_or_b32_e32 v112, 6, v100
	v_or_b32_e32 v113, 7, v100
	v_add_u32_e32 v114, -4, v11
	v_add_u32_e32 v115, -8, v11
	v_add_u32_e32 v116, -16, v11
	v_subrev_u32_e32 v117, 32, v11
	v_subrev_u32_e32 v118, 64, v11
	v_add_u32_e32 v119, 0xffffff80, v11
	v_add_u32_e32 v121, 0x100, v120
	v_add_u32_e32 v123, 0x200, v120
	v_add_u32_e32 v124, 0x300, v120
	v_add_u32_e32 v125, 0x400, v120
	v_add_u32_e32 v126, 0x500, v120
	v_add_u32_e32 v127, 0x600, v120
	v_add_u32_e32 v128, 0x700, v120
	v_add_u32_e32 v129, 0x800, v120
	v_add_u32_e32 v130, 0x900, v120
	v_add_u32_e32 v131, 0xa00, v120
	v_add_u32_e32 v132, 0xb00, v120
	v_add_u32_e32 v133, 0xc00, v120
	v_add_u32_e32 v134, 0xd00, v120
	v_add_u32_e32 v135, 0xe00, v120
	v_add_u32_e32 v136, 0xf00, v120
	v_xor_b32_e32 v137, 4, v11
	v_xor_b32_e32 v138, 8, v11
	v_xor_b32_e32 v139, 16, v11
	v_xor_b32_e32 v140, 32, v11
	v_xor_b32_e32 v141, 64, v11
	v_xor_b32_e32 v142, 0x80, v11
	s_ashr_i32 s31, s30, 31
	s_ashr_i32 s15, s14, 31
	v_writelane_b32 v255, s3, 57
	s_ashr_i32 s17, s16, 31
	v_add_u32_e32 v195, 16, v194
	v_add_u32_e32 v204, 32, v194
	v_add_u32_e32 v205, 48, v194
	v_add_u32_e32 v206, 64, v194
	v_add_u32_e32 v207, 0x50, v194
	v_add_u32_e32 v208, 0x60, v194
	v_add_u32_e32 v209, 0x70, v194
	v_lshl_or_b32 v210, v5, 9, v6
	v_lshl_add_u64 v[84:85], s[0:1], 0, v[196:197]
	v_add_u32_e32 v196, v7, v8
	v_add_u32_e32 v214, v15, v0
	s_mov_b32 s2, s46
	s_branch .LBB0_672

; __device__ __forceinline__ unsigned f2bf(float f) { return pk2(f, 0.f) & 0xffffu; }
; #define MFMA16(a, b, c) __builtin_amdgcn_mfma_f32_16x16x32_bf16((a), (b), (c), 0, 0, 0)
; __global__ void __launch_bounds__(512, 2) fwd_megakernel(Params kp_) {
;     ...
;                                 for (int q4 = 0; q4 < 4; ++q4) { const int idx = wave * 4 + q4, kind = idx >> 4, ti = (idx >> 2) & 3, tj = idx & 3;
;                                     const bf16* Ab = (kind == 0 ? kbf : qbf) + (ti * 16 + r16) * 136 + g4 * 8; const bf16* Bb = kbf + (tj * 16 + r16) * 136 + g4 * 8;
;                                     f32x4 acc = {0.f, 0.f, 0.f, 0.f};
; #pragma unroll
;                                     for (int k0 = 0; k0 < 128; k0 += 32) acc = MFMA16(*(const bf16x8*)(Ab + k0), *(const bf16x8*)(Bb + k0), acc);
;                                     const int jj = tj * 16 + r16; const float gj = gc[jj];
; #pragma unroll
;                                     for (int j = 0; j < 4; ++j) { const int i = ti * 16 + g4 * 4 + j; const float dec = __expf(fminf(gc[i] - gj, 0.f));
;                                         if (kind == 0) Ls[i * 64 + jj] = (i > jj) ? acc[j] * bet[i] * dec : 0.f;
;                                         else AAbuf[(size_t)item * 4096 + i * 64 + jj] = (bf16)f2bf((i >= jj) ? acc[j] * dec : 0.f); }
.LBB0_702:
	s_add_u32 s20, s20, 0x400
	s_addc_u32 s21, s21, 0
	v_add_u32_e32 v11, 0x80, v11
	v_add_u32_e32 v10, 32, v10
	v_add_u32_e32 v9, 0x80, v9
	s_cmpk_eq_i32 s20, 0x800
	v_add_u32_e32 v8, 0x2200, v8
	s_cbranch_scc1 .LBB0_750

; __device__ __forceinline__ unsigned f2bf(float f) { return pk2(f, 0.f) & 0xffffu; }
; #define MFMA16(a, b, c) __builtin_amdgcn_mfma_f32_16x16x32_bf16((a), (b), (c), 0, 0, 0)
; __global__ void __launch_bounds__(512, 2) fwd_megakernel(Params kp_) {
;     ...
;                                 for (int q4 = 0; q4 < 4; ++q4) { const int idx = wave * 4 + q4, kind = idx >> 4, ti = (idx >> 2) & 3, tj = idx & 3;
;                                     const bf16* Ab = (kind == 0 ? kbf : qbf) + (ti * 16 + r16) * 136 + g4 * 8; const bf16* Bb = kbf + (tj * 16 + r16) * 136 + g4 * 8;
;                                     f32x4 acc = {0.f, 0.f, 0.f, 0.f};
; #pragma unroll
;                                     for (int k0 = 0; k0 < 128; k0 += 32) acc = MFMA16(*(const bf16x8*)(Ab + k0), *(const bf16x8*)(Bb + k0), acc);
;                                     const int jj = tj * 16 + r16; const float gj = gc[jj];
; #pragma unroll
;                                     for (int j = 0; j < 4; ++j) { const int i = ti * 16 + g4 * 4 + j; const float dec = __expf(fminf(gc[i] - gj, 0.f));
;                                         if (kind == 0) Ls[i * 64 + jj] = (i > jj) ? acc[j] * bet[i] * dec : 0.f;
;                                         else AAbuf[(size_t)item * 4096 + i * 64 + jj] = (bf16)f2bf((i >= jj) ? acc[j] * dec : 0.f); }
.LBB0_709:
	ds_read_b32 v0, v186
	v_cndmask_b32_e64 v4, 0, 1, s[34:35]
	s_mov_b64 s[0:1], -1
	v_cmp_ne_u32_e64 s[26:27], 1, v4
	s_andn2_b64 vcc, exec, s[34:35]
	s_waitcnt lgkmcnt(0)
	v_sub_f32_e32 v0, v0, v14
	v_min_f32_e32 v0, 0, v0
	v_mul_f32_e32 v0, 0x3fb8aa3b, v0
	v_exp_f32_e32 v0, v0
	v_lshl_add_u64 v[4:5], v[84:85], 0, s[20:21]
	s_cbranch_vccnz .LBB0_711
	v_mul_f32_e32 v15, v1, v0
	v_cvt_pk_bf16_f32 v15, v15, s0
	v_cmp_ge_u32_e32 vcc, v185, v10
	s_mov_b64 s[0:1], 0
	s_nop 0
	v_cndmask_b32_e32 v15, 0, v15, vcc
	global_store_short v[4:5], v15, off offset:-240

; __device__ __forceinline__ unsigned f2bf(float f) { return pk2(f, 0.f) & 0xffffu; }
; #define MFMA16(a, b, c) __builtin_amdgcn_mfma_f32_16x16x32_bf16((a), (b), (c), 0, 0, 0)
; __global__ void __launch_bounds__(512, 2) fwd_megakernel(Params kp_) {
;     ...
;                                 for (int q4 = 0; q4 < 4; ++q4) { const int idx = wave * 4 + q4, kind = idx >> 4, ti = (idx >> 2) & 3, tj = idx & 3;
;                                     const bf16* Ab = (kind == 0 ? kbf : qbf) + (ti * 16 + r16) * 136 + g4 * 8; const bf16* Bb = kbf + (tj * 16 + r16) * 136 + g4 * 8;
;                                     f32x4 acc = {0.f, 0.f, 0.f, 0.f};
; #pragma unroll
;                                     for (int k0 = 0; k0 < 128; k0 += 32) acc = MFMA16(*(const bf16x8*)(Ab + k0), *(const bf16x8*)(Bb + k0), acc);
;                                     const int jj = tj * 16 + r16; const float gj = gc[jj];
; #pragma unroll
;                                     for (int j = 0; j < 4; ++j) { const int i = ti * 16 + g4 * 4 + j; const float dec = __expf(fminf(gc[i] - gj, 0.f));
;                                         if (kind == 0) Ls[i * 64 + jj] = (i > jj) ? acc[j] * bet[i] * dec : 0.f;
;                                         else AAbuf[(size_t)item * 4096 + i * 64 + jj] = (bf16)f2bf((i >= jj) ? acc[j] * dec : 0.f); }
.LBB0_715:
	ds_read_b32 v0, v189
	s_and_b64 vcc, exec, s[26:27]
	s_mov_b64 s[0:1], -1
	s_waitcnt lgkmcnt(0)
	v_sub_f32_e32 v0, v0, v14
	v_min_f32_e32 v0, 0, v0
	v_mul_f32_e32 v0, 0x3fb8aa3b, v0
	v_exp_f32_e32 v0, v0
	s_cbranch_vccnz .LBB0_717
	v_mul_f32_e32 v1, v2, v0
	v_cvt_pk_bf16_f32 v1, v1, s0
	v_cmp_ge_u32_e32 vcc, v188, v10
	s_mov_b64 s[0:1], 0
	s_nop 0
	v_cndmask_b32_e32 v1, 0, v1, vcc
	global_store_short v[4:5], v1, off offset:-224

; __device__ __forceinline__ unsigned f2bf(float f) { return pk2(f, 0.f) & 0xffffu; }
; #define MFMA16(a, b, c) __builtin_amdgcn_mfma_f32_16x16x32_bf16((a), (b), (c), 0, 0, 0)
; __global__ void __launch_bounds__(512, 2) fwd_megakernel(Params kp_) {
;     ...
;                                 for (int q4 = 0; q4 < 4; ++q4) { const int idx = wave * 4 + q4, kind = idx >> 4, ti = (idx >> 2) & 3, tj = idx & 3;
;                                     const bf16* Ab = (kind == 0 ? kbf : qbf) + (ti * 16 + r16) * 136 + g4 * 8; const bf16* Bb = kbf + (tj * 16 + r16) * 136 + g4 * 8;
;                                     f32x4 acc = {0.f, 0.f, 0.f, 0.f};
; #pragma unroll
;                                     for (int k0 = 0; k0 < 128; k0 += 32) acc = MFMA16(*(const bf16x8*)(Ab + k0), *(const bf16x8*)(Bb + k0), acc);
;                                     const int jj = tj * 16 + r16; const float gj = gc[jj];
; #pragma unroll
;                                     for (int j = 0; j < 4; ++j) { const int i = ti * 16 + g4 * 4 + j; const float dec = __expf(fminf(gc[i] - gj, 0.f));
;                                         if (kind == 0) Ls[i * 64 + jj] = (i > jj) ? acc[j] * bet[i] * dec : 0.f;
;                                         else AAbuf[(size_t)item * 4096 + i * 64 + jj] = (bf16)f2bf((i >= jj) ? acc[j] * dec : 0.f); }
.LBB0_721:
	ds_read_b32 v0, v192
	s_and_b64 vcc, exec, s[26:27]
	s_mov_b64 s[0:1], -1
	s_waitcnt lgkmcnt(0)
	v_sub_f32_e32 v0, v0, v14
	v_min_f32_e32 v0, 0, v0
	v_mul_f32_e32 v0, 0x3fb8aa3b, v0
	v_exp_f32_e32 v0, v0
	s_cbranch_vccnz .LBB0_723
	v_mul_f32_e32 v1, v3, v0
	v_cvt_pk_bf16_f32 v1, v1, s0
	v_cmp_ge_u32_e32 vcc, v191, v10
	s_mov_b64 s[0:1], 0
	s_nop 0
	v_cndmask_b32_e32 v1, 0, v1, vcc
	global_store_short v[4:5], v1, off offset:-208

; __device__ __forceinline__ unsigned f2bf(float f) { return pk2(f, 0.f) & 0xffffu; }
; #define MFMA16(a, b, c) __builtin_amdgcn_mfma_f32_16x16x32_bf16((a), (b), (c), 0, 0, 0)
; __global__ void __launch_bounds__(512, 2) fwd_megakernel(Params kp_) {
;     ...
;                                     const bf16* Ab = (kind == 0 ? kbf : qbf) + (ti * 16 + r16) * 136 + g4 * 8; const bf16* Bb = kbf + (tj * 16 + r16) * 136 + g4 * 8;
;                                     f32x4 acc = {0.f, 0.f, 0.f, 0.f};
; #pragma unroll
;                                     for (int k0 = 0; k0 < 128; k0 += 32) acc = MFMA16(*(const bf16x8*)(Ab + k0), *(const bf16x8*)(Bb + k0), acc);
;                                     const int jj = tj * 16 + r16; const float gj = gc[jj];
; #pragma unroll
;                                     for (int j = 0; j < 4; ++j) { const int i = ti * 16 + g4 * 4 + j; const float dec = __expf(fminf(gc[i] - gj, 0.f));
;                                         if (kind == 0) Ls[i * 64 + jj] = (i > jj) ? acc[j] * bet[i] * dec : 0.f;
;                                         else AAbuf[(size_t)item * 4096 + i * 64 + jj] = (bf16)f2bf((i >= jj) ? acc[j] * dec : 0.f); }
.LBB0_727:
	v_add_u32_e32 v15, 0x1d500, v12
	ds_read_b128 v[0:3], v102
	ds_read_b128 v[16:19], v15
	v_add_u32_e32 v15, 0x1d540, v12
	ds_read_b128 v[20:23], v15
	v_add_u32_e32 v15, 0x1d580, v12
	s_waitcnt lgkmcnt(1)
	v_mfma_f32_16x16x32_bf16 v[0:3], v[0:3], v[16:19], 0
	ds_read_b128 v[16:19], v102 offset:64
	v_add_u32_e32 v12, 0x1d5c0, v12
	v_add_u32_e32 v14, 16, v10
	s_mov_b64 s[22:23], -1
	s_and_b64 vcc, exec, s[26:27]
	v_cmp_ge_u32_e64 s[0:1], v103, v14
	s_waitcnt lgkmcnt(0)
	v_mfma_f32_16x16x32_bf16 v[0:3], v[16:19], v[20:23], v[0:3]
	ds_read_b128 v[16:19], v102 offset:128
	ds_read_b128 v[20:23], v15
	s_waitcnt lgkmcnt(0)
	v_mfma_f32_16x16x32_bf16 v[0:3], v[16:19], v[20:23], v[0:3]
	ds_read_b128 v[16:19], v102 offset:192
	ds_read_b128 v[20:23], v12
	v_add_u32_e32 v12, 0x20840, v13
	ds_read_b32 v12, v12
	ds_read_b32 v13, v183
	s_waitcnt lgkmcnt(2)
	v_mfma_f32_16x16x32_bf16 v[0:3], v[16:19], v[20:23], v[0:3]
	s_waitcnt lgkmcnt(0)
	v_sub_f32_e32 v13, v13, v12
	v_min_f32_e32 v13, 0, v13
	v_mul_f32_e32 v13, 0x3fb8aa3b, v13
	v_exp_f32_e32 v13, v13
	s_cbranch_vccnz .LBB0_729
	s_nop 1
	v_mul_f32_e32 v15, v0, v13
	v_cvt_pk_bf16_f32 v15, v15, s0
	v_add_co_u32_e32 v6, vcc, 0x4800000, v6
	v_cndmask_b32_e64 v15, 0, v15, s[0:1]
	s_nop 0
	v_addc_co_u32_e32 v7, vcc, 0, v7, vcc
	s_mov_b64 s[22:23], 0
	global_store_short v[6:7], v15, off offset:512

; __device__ __forceinline__ unsigned f2bf(float f) { return pk2(f, 0.f) & 0xffffu; }
; #define MFMA16(a, b, c) __builtin_amdgcn_mfma_f32_16x16x32_bf16((a), (b), (c), 0, 0, 0)
; __global__ void __launch_bounds__(512, 2) fwd_megakernel(Params kp_) {
;     ...
;                                 for (int q4 = 0; q4 < 4; ++q4) { const int idx = wave * 4 + q4, kind = idx >> 4, ti = (idx >> 2) & 3, tj = idx & 3;
;                                     const bf16* Ab = (kind == 0 ? kbf : qbf) + (ti * 16 + r16) * 136 + g4 * 8; const bf16* Bb = kbf + (tj * 16 + r16) * 136 + g4 * 8;
;                                     f32x4 acc = {0.f, 0.f, 0.f, 0.f};
; #pragma unroll
;                                     for (int k0 = 0; k0 < 128; k0 += 32) acc = MFMA16(*(const bf16x8*)(Ab + k0), *(const bf16x8*)(Bb + k0), acc);
;                                     const int jj = tj * 16 + r16; const float gj = gc[jj];
; #pragma unroll
;                                     for (int j = 0; j < 4; ++j) { const int i = ti * 16 + g4 * 4 + j; const float dec = __expf(fminf(gc[i] - gj, 0.f));
;                                         if (kind == 0) Ls[i * 64 + jj] = (i > jj) ? acc[j] * bet[i] * dec : 0.f;
;                                         else AAbuf[(size_t)item * 4096 + i * 64 + jj] = (bf16)f2bf((i >= jj) ? acc[j] * dec : 0.f); }
.LBB0_733:
	ds_read_b32 v0, v186
	s_and_b64 vcc, exec, s[26:27]
	s_mov_b64 s[0:1], -1
	s_waitcnt lgkmcnt(0)
	v_sub_f32_e32 v0, v0, v12
	v_min_f32_e32 v0, 0, v0
	v_mul_f32_e32 v0, 0x3fb8aa3b, v0
	v_exp_f32_e32 v0, v0
	s_cbranch_vccnz .LBB0_735
	v_mul_f32_e32 v6, v1, v0
	v_cvt_pk_bf16_f32 v6, v6, s0
	v_cmp_ge_u32_e32 vcc, v185, v14
	s_mov_b64 s[0:1], 0
	s_nop 0
	v_cndmask_b32_e32 v6, 0, v6, vcc
	global_store_short v[4:5], v6, off offset:272

; __device__ __forceinline__ unsigned f2bf(float f) { return pk2(f, 0.f) & 0xffffu; }
; #define MFMA16(a, b, c) __builtin_amdgcn_mfma_f32_16x16x32_bf16((a), (b), (c), 0, 0, 0)
; __global__ void __launch_bounds__(512, 2) fwd_megakernel(Params kp_) {
;     ...
;                                 for (int q4 = 0; q4 < 4; ++q4) { const int idx = wave * 4 + q4, kind = idx >> 4, ti = (idx >> 2) & 3, tj = idx & 3;
;                                     const bf16* Ab = (kind == 0 ? kbf : qbf) + (ti * 16 + r16) * 136 + g4 * 8; const bf16* Bb = kbf + (tj * 16 + r16) * 136 + g4 * 8;
;                                     f32x4 acc = {0.f, 0.f, 0.f, 0.f};
; #pragma unroll
;                                     for (int k0 = 0; k0 < 128; k0 += 32) acc = MFMA16(*(const bf16x8*)(Ab + k0), *(const bf16x8*)(Bb + k0), acc);
;                                     const int jj = tj * 16 + r16; const float gj = gc[jj];
; #pragma unroll
;                                     for (int j = 0; j < 4; ++j) { const int i = ti * 16 + g4 * 4 + j; const float dec = __expf(fminf(gc[i] - gj, 0.f));
;                                         if (kind == 0) Ls[i * 64 + jj] = (i > jj) ? acc[j] * bet[i] * dec : 0.f;
;                                         else AAbuf[(size_t)item * 4096 + i * 64 + jj] = (bf16)f2bf((i >= jj) ? acc[j] * dec : 0.f); }
.LBB0_739:
	ds_read_b32 v0, v189
	s_and_b64 vcc, exec, s[26:27]
	s_mov_b64 s[0:1], -1
	s_waitcnt lgkmcnt(0)
	v_sub_f32_e32 v0, v0, v12
	v_min_f32_e32 v0, 0, v0
	v_mul_f32_e32 v0, 0x3fb8aa3b, v0
	v_exp_f32_e32 v0, v0
	s_cbranch_vccnz .LBB0_741
	v_mul_f32_e32 v1, v2, v0
	v_cvt_pk_bf16_f32 v1, v1, s0
	v_cmp_ge_u32_e32 vcc, v188, v14
	s_mov_b64 s[0:1], 0
	s_nop 0
	v_cndmask_b32_e32 v1, 0, v1, vcc
	global_store_short v[4:5], v1, off offset:288

; __device__ __forceinline__ unsigned f2bf(float f) { return pk2(f, 0.f) & 0xffffu; }
; #define MFMA16(a, b, c) __builtin_amdgcn_mfma_f32_16x16x32_bf16((a), (b), (c), 0, 0, 0)
; __global__ void __launch_bounds__(512, 2) fwd_megakernel(Params kp_) {
;     ...
;                                 for (int q4 = 0; q4 < 4; ++q4) { const int idx = wave * 4 + q4, kind = idx >> 4, ti = (idx >> 2) & 3, tj = idx & 3;
;                                     const bf16* Ab = (kind == 0 ? kbf : qbf) + (ti * 16 + r16) * 136 + g4 * 8; const bf16* Bb = kbf + (tj * 16 + r16) * 136 + g4 * 8;
;                                     f32x4 acc = {0.f, 0.f, 0.f, 0.f};
; #pragma unroll
;                                     for (int k0 = 0; k0 < 128; k0 += 32) acc = MFMA16(*(const bf16x8*)(Ab + k0), *(const bf16x8*)(Bb + k0), acc);
;                                     const int jj = tj * 16 + r16; const float gj = gc[jj];
; #pragma unroll
;                                     for (int j = 0; j < 4; ++j) { const int i = ti * 16 + g4 * 4 + j; const float dec = __expf(fminf(gc[i] - gj, 0.f));
;                                         if (kind == 0) Ls[i * 64 + jj] = (i > jj) ? acc[j] * bet[i] * dec : 0.f;
;                                         else AAbuf[(size_t)item * 4096 + i * 64 + jj] = (bf16)f2bf((i >= jj) ? acc[j] * dec : 0.f); }
.LBB0_745:
	ds_read_b32 v0, v192
	s_and_b64 vcc, exec, s[26:27]
	s_mov_b64 s[0:1], -1
	s_waitcnt lgkmcnt(0)
	v_sub_f32_e32 v0, v0, v12
	v_min_f32_e32 v0, 0, v0
	v_mul_f32_e32 v0, 0x3fb8aa3b, v0
	v_exp_f32_e32 v0, v0
	s_cbranch_vccnz .LBB0_747
	v_mul_f32_e32 v1, v3, v0
	v_cvt_pk_bf16_f32 v1, v1, s0
	v_cmp_ge_u32_e32 vcc, v191, v14
	s_mov_b64 s[0:1], 0
	s_nop 0
	v_cndmask_b32_e32 v1, 0, v1, vcc
	global_store_short v[4:5], v1, off offset:304

; #define LBAR() asm volatile("s_waitcnt lgkmcnt(0)\n\ts_barrier" ::: "memory")
; __global__ void __launch_bounds__(512, 2) fwd_megakernel(Params kp_) {
;     ...
;                             LBAR();
;                             LBAR();
;                             if (tid < 256) {
;                                 const f32x4* Ls4 = (const f32x4*)qc; const int c = tid; const bool isu = c < 128; float* X = isu ? (vc + c) : (kc + (c - 128));
;                                 bf16* dst = (isu ? Ubuf : WNbuf) + (size_t)item * 8192 + (isu ? c : c - 128);
;     ...
;                             } else {
;                                 const int d = tid & 127, ih = (tid >> 7) & 1; const float gl = gc[63];
;                                 bf16* kd = KDT + (size_t)item * 8192 + d * 64 + ih * 32;
.LBB0_750:
	s_waitcnt lgkmcnt(0)
	s_barrier
	s_waitcnt lgkmcnt(0)
	s_barrier
	s_and_saveexec_b64 s[0:1], s[42:43]
	s_xor_b64 s[0:1], exec, s[0:1]
	s_cbranch_execz .LBB0_752
; __device__ __forceinline__ unsigned pk2(float lo, float hi) { const f32x2_t v = {lo, hi}; const bf16x2_t b = __builtin_convertvector(v, bf16x2_t); return __builtin_bit_cast(unsigned, b); }
; __global__ void __launch_bounds__(512, 2) fwd_megakernel(Params kp_) {
;     ...
;                                 const int d = tid & 127, ih = (tid >> 7) & 1; const float gl = gc[63];
;                                 bf16* kd = KDT + (size_t)item * 8192 + d * 64 + ih * 32;
; #pragma unroll
;                                 for (int c8 = 0; c8 < 4; ++c8) { float e[8];
; #pragma unroll
;                                     for (int q = 0; q < 8; ++q) { const int i0 = ih * 32 + c8 * 8 + q; e[q] = bf2f(kbf[i0 * 136 + d]) * __expf(gl - gc[i0]); }
;                                     u32x4 w; w.x = pk2(e[0], e[1]); w.y = pk2(e[2], e[3]); w.z = pk2(e[4], e[5]); w.w = pk2(e[6], e[7]);
;                                     *(u32x4*)(kd + c8 * 8) = w; }
	v_readlane_b32 s3, v254, 32
	ds_read_b128 v[2:5], v194
	s_nop 0
	v_mov_b32_e32 v0, s3
	ds_read_b32 v6, v0
	ds_read_u16 v7, v214
	ds_read_u16 v8, v214 offset:272
	v_lshl_add_u64 v[0:1], v[78:79], 0, s[18:19]
	s_waitcnt lgkmcnt(2)
	v_sub_f32_e32 v2, v6, v2
	v_sub_f32_e32 v3, v6, v3
	v_mul_f32_e32 v2, 0x3fb8aa3b, v2
	v_mul_f32_e32 v3, 0x3fb8aa3b, v3
	v_exp_f32_e32 v2, v2
	v_exp_f32_e32 v3, v3
	s_waitcnt lgkmcnt(0)
	v_lshlrev_b32_e32 v9, 16, v8
	v_lshlrev_b32_e32 v8, 16, v7
	v_sub_f32_e32 v4, v6, v4
	v_pk_mul_f32 v[2:3], v[2:3], v[8:9]
	v_sub_f32_e32 v5, v6, v5
	ds_read_u16 v7, v214 offset:544
	ds_read_u16 v8, v214 offset:816
	v_mul_f32_e32 v4, 0x3fb8aa3b, v4
	v_mul_f32_e32 v5, 0x3fb8aa3b, v5
	v_exp_f32_e32 v4, v4
	v_exp_f32_e32 v5, v5
	s_waitcnt lgkmcnt(0)
	v_lshlrev_b32_e32 v9, 16, v8
	v_lshlrev_b32_e32 v8, 16, v7
	v_cvt_pk_bf16_f32 v2, v2, v3
	v_pk_mul_f32 v[4:5], v[4:5], v[8:9]
	ds_read_b128 v[8:11], v195
	v_cvt_pk_bf16_f32 v3, v4, v5
	s_waitcnt lgkmcnt(0)
	v_sub_f32_e32 v7, v6, v8
	v_mul_f32_e32 v7, 0x3fb8aa3b, v7
	v_exp_f32_e32 v8, v7
	v_sub_f32_e32 v7, v6, v9
	v_mul_f32_e32 v7, 0x3fb8aa3b, v7
	v_exp_f32_e32 v9, v7
	ds_read_u16 v7, v214 offset:1088
	ds_read_u16 v12, v214 offset:1360
	s_waitcnt lgkmcnt(0)
	v_lshlrev_b32_e32 v13, 16, v12
	v_lshlrev_b32_e32 v12, 16, v7
	v_sub_f32_e32 v7, v6, v10
	v_mul_f32_e32 v7, 0x3fb8aa3b, v7
	v_exp_f32_e32 v10, v7
	v_sub_f32_e32 v7, v6, v11
	v_mul_f32_e32 v7, 0x3fb8aa3b, v7
	v_pk_mul_f32 v[8:9], v[8:9], v[12:13]
	v_exp_f32_e32 v11, v7
	ds_read_u16 v7, v214 offset:1632
	ds_read_u16 v12, v214 offset:1904
	v_cvt_pk_bf16_f32 v4, v8, v9
	s_waitcnt lgkmcnt(0)
	v_lshlrev_b32_e32 v13, 16, v12
	v_lshlrev_b32_e32 v12, 16, v7
	v_pk_mul_f32 v[10:11], v[10:11], v[12:13]
	s_nop 0
	v_cvt_pk_bf16_f32 v5, v10, v11
	global_store_dwordx4 v[0:1], v[2:5], off
	ds_read_b128 v[2:5], v204
	ds_read_u16 v7, v214 offset:2176
	ds_read_u16 v8, v214 offset:2448
	s_waitcnt lgkmcnt(2)
	v_sub_f32_e32 v2, v6, v2
	v_sub_f32_e32 v3, v6, v3
	v_mul_f32_e32 v2, 0x3fb8aa3b, v2
	v_mul_f32_e32 v3, 0x3fb8aa3b, v3
	v_exp_f32_e32 v2, v2
	v_exp_f32_e32 v3, v3
	s_waitcnt lgkmcnt(0)
	v_lshlrev_b32_e32 v9, 16, v8
	v_lshlrev_b32_e32 v8, 16, v7
	v_sub_f32_e32 v4, v6, v4
	v_pk_mul_f32 v[2:3], v[2:3], v[8:9]
	v_sub_f32_e32 v5, v6, v5
	ds_read_u16 v7, v214 offset:2720
	ds_read_u16 v8, v214 offset:2992
	v_mul_f32_e32 v4, 0x3fb8aa3b, v4
	v_mul_f32_e32 v5, 0x3fb8aa3b, v5
	v_exp_f32_e32 v4, v4
	v_exp_f32_e32 v5, v5
	s_waitcnt lgkmcnt(0)
	v_lshlrev_b32_e32 v9, 16, v8
	v_lshlrev_b32_e32 v8, 16, v7
	v_cvt_pk_bf16_f32 v2, v2, v3
	v_pk_mul_f32 v[4:5], v[4:5], v[8:9]
	ds_read_b128 v[8:11], v205
	v_cvt_pk_bf16_f32 v3, v4, v5
	s_waitcnt lgkmcnt(0)
	v_sub_f32_e32 v7, v6, v8
	v_mul_f32_e32 v7, 0x3fb8aa3b, v7
	v_exp_f32_e32 v8, v7
	v_sub_f32_e32 v7, v6, v9
	v_mul_f32_e32 v7, 0x3fb8aa3b, v7
	v_exp_f32_e32 v9, v7
	ds_read_u16 v7, v214 offset:3264
	ds_read_u16 v12, v214 offset:3536
	s_waitcnt lgkmcnt(0)
	v_lshlrev_b32_e32 v13, 16, v12
	v_lshlrev_b32_e32 v12, 16, v7
	v_sub_f32_e32 v7, v6, v10
	v_mul_f32_e32 v7, 0x3fb8aa3b, v7
	v_exp_f32_e32 v10, v7
	v_sub_f32_e32 v7, v6, v11
	v_mul_f32_e32 v7, 0x3fb8aa3b, v7
	v_pk_mul_f32 v[8:9], v[8:9], v[12:13]
	v_exp_f32_e32 v11, v7
	ds_read_u16 v7, v214 offset:3808
	ds_read_u16 v12, v214 offset:4080
	v_cvt_pk_bf16_f32 v4, v8, v9
	s_waitcnt lgkmcnt(0)
	v_lshlrev_b32_e32 v13, 16, v12
	v_lshlrev_b32_e32 v12, 16, v7
	v_pk_mul_f32 v[10:11], v[10:11], v[12:13]
	s_nop 0
	v_cvt_pk_bf16_f32 v5, v10, v11
	global_store_dwordx4 v[0:1], v[2:5], off offset:256
	ds_read_b128 v[2:5], v206
	ds_read_u16 v7, v214 offset:4352
	ds_read_u16 v8, v214 offset:4624
	s_waitcnt lgkmcnt(2)
	v_sub_f32_e32 v2, v6, v2
	v_sub_f32_e32 v3, v6, v3
	v_mul_f32_e32 v2, 0x3fb8aa3b, v2
	v_mul_f32_e32 v3, 0x3fb8aa3b, v3
	v_exp_f32_e32 v2, v2
	v_exp_f32_e32 v3, v3
	s_waitcnt lgkmcnt(0)
	v_lshlrev_b32_e32 v9, 16, v8
	v_lshlrev_b32_e32 v8, 16, v7
	v_sub_f32_e32 v4, v6, v4
	v_pk_mul_f32 v[2:3], v[2:3], v[8:9]
	v_sub_f32_e32 v5, v6, v5
	ds_read_u16 v7, v214 offset:4896
	ds_read_u16 v8, v214 offset:5168
	v_mul_f32_e32 v4, 0x3fb8aa3b, v4
	v_mul_f32_e32 v5, 0x3fb8aa3b, v5
	v_exp_f32_e32 v4, v4
	v_exp_f32_e32 v5, v5
	s_waitcnt lgkmcnt(0)
	v_lshlrev_b32_e32 v9, 16, v8
	v_lshlrev_b32_e32 v8, 16, v7
	v_cvt_pk_bf16_f32 v2, v2, v3
	v_pk_mul_f32 v[4:5], v[4:5], v[8:9]
	ds_read_b128 v[8:11], v207
	v_cvt_pk_bf16_f32 v3, v4, v5
	s_waitcnt lgkmcnt(0)
	v_sub_f32_e32 v7, v6, v8
	v_mul_f32_e32 v7, 0x3fb8aa3b, v7
	v_exp_f32_e32 v8, v7
	v_sub_f32_e32 v7, v6, v9
	v_mul_f32_e32 v7, 0x3fb8aa3b, v7
	v_exp_f32_e32 v9, v7
	ds_read_u16 v7, v214 offset:5440
	ds_read_u16 v12, v214 offset:5712
	s_waitcnt lgkmcnt(0)
	v_lshlrev_b32_e32 v13, 16, v12
	v_lshlrev_b32_e32 v12, 16, v7
	v_sub_f32_e32 v7, v6, v10
	v_mul_f32_e32 v7, 0x3fb8aa3b, v7
	v_exp_f32_e32 v10, v7
	v_sub_f32_e32 v7, v6, v11
	v_mul_f32_e32 v7, 0x3fb8aa3b, v7
	v_pk_mul_f32 v[8:9], v[8:9], v[12:13]
	v_exp_f32_e32 v11, v7
	ds_read_u16 v7, v214 offset:5984
	ds_read_u16 v12, v214 offset:6256
	v_cvt_pk_bf16_f32 v4, v8, v9
	s_waitcnt lgkmcnt(0)
	v_lshlrev_b32_e32 v13, 16, v12
	v_lshlrev_b32_e32 v12, 16, v7
	v_pk_mul_f32 v[10:11], v[10:11], v[12:13]
	s_nop 0
	v_cvt_pk_bf16_f32 v5, v10, v11
	global_store_dwordx4 v[0:1], v[2:5], off offset:512
	ds_read_b128 v[2:5], v208
	ds_read_u16 v7, v214 offset:6528
	ds_read_u16 v8, v214 offset:6800
	s_waitcnt lgkmcnt(2)
	v_sub_f32_e32 v2, v6, v2
	v_sub_f32_e32 v3, v6, v3
	v_mul_f32_e32 v2, 0x3fb8aa3b, v2
	v_mul_f32_e32 v3, 0x3fb8aa3b, v3
	v_exp_f32_e32 v2, v2
	v_exp_f32_e32 v3, v3
	s_waitcnt lgkmcnt(0)
	v_lshlrev_b32_e32 v9, 16, v8
	v_lshlrev_b32_e32 v8, 16, v7
	v_sub_f32_e32 v4, v6, v4
	v_pk_mul_f32 v[2:3], v[2:3], v[8:9]
	v_sub_f32_e32 v5, v6, v5
	ds_read_u16 v7, v214 offset:7072
	ds_read_u16 v8, v214 offset:7344
	v_mul_f32_e32 v4, 0x3fb8aa3b, v4
	v_mul_f32_e32 v5, 0x3fb8aa3b, v5
	v_exp_f32_e32 v4, v4
	v_exp_f32_e32 v5, v5
	s_waitcnt lgkmcnt(0)
	v_lshlrev_b32_e32 v9, 16, v8
	v_lshlrev_b32_e32 v8, 16, v7
	v_cvt_pk_bf16_f32 v2, v2, v3
	v_pk_mul_f32 v[4:5], v[4:5], v[8:9]
	ds_read_b128 v[8:11], v209
	v_cvt_pk_bf16_f32 v3, v4, v5
	s_waitcnt lgkmcnt(0)
	v_sub_f32_e32 v7, v6, v8
	v_mul_f32_e32 v7, 0x3fb8aa3b, v7
	v_exp_f32_e32 v8, v7
	v_sub_f32_e32 v7, v6, v9
	v_mul_f32_e32 v7, 0x3fb8aa3b, v7
	v_exp_f32_e32 v9, v7
	ds_read_u16 v7, v214 offset:7616
	ds_read_u16 v12, v214 offset:7888
	s_waitcnt lgkmcnt(0)
	v_lshlrev_b32_e32 v13, 16, v12
	v_lshlrev_b32_e32 v12, 16, v7
	v_sub_f32_e32 v7, v6, v10
	v_sub_f32_e32 v6, v6, v11
	v_mul_f32_e32 v7, 0x3fb8aa3b, v7
	v_mul_f32_e32 v6, 0x3fb8aa3b, v6
	v_exp_f32_e32 v10, v7
	v_exp_f32_e32 v11, v6
	ds_read_u16 v6, v214 offset:8160
	ds_read_u16 v7, v214 offset:8432
	v_pk_mul_f32 v[8:9], v[8:9], v[12:13]
	s_waitcnt lgkmcnt(1)
	v_lshlrev_b32_e32 v6, 16, v6
	s_waitcnt lgkmcnt(0)
	v_lshlrev_b32_e32 v7, 16, v7
	v_pk_mul_f32 v[6:7], v[10:11], v[6:7]
	v_cvt_pk_bf16_f32 v4, v8, v9
	v_cvt_pk_bf16_f32 v5, v6, v7
	global_store_dwordx4 v[0:1], v[2:5], off offset:768

; __global__ void __launch_bounds__(512, 2) fwd_megakernel(Params kp_) {
;     ...
;                         for (int item = bid; item < 128; item += G) {
;                             const int xk_ = item >> 3, blk = xk_ & 7, bh = (item & 7) * 2 + (xk_ >> 3), h = bh & 3, b = bh >> 2, e0 = blk * 16;
;                             bf16* ST = (bf16*)lds; bf16* VT = ST + 16 * 136;
;                             for (int i = tid; i < 16 * 136; i += 512) ST[i] = 0;
;                             f32x4 Sacc = {0.f, 0.f, 0.f, 0.f};
;                             __syncthreads();
;                             const int rt = wave & 3; const bool lo = wave < 4;
;                             bf16x8 fa[4], fb[2], fk[2]; float uv[4]; float eg;
;     ...
;                             bf16x8 fa1[4], fb1[2], fk1[2]; float uv1[4]; float eg1;
;                             bf16x8 fa2[4], fb2[2], fk2[2]; float uv2[4]; float eg2;
;                             GS_LOAD(fa, fb, fk, uv, eg, 0); GS_LOAD(fa1, fb1, fk1, uv1, eg1, 1);
.LBB0_843:
	s_or_b64 exec, exec, s[0:1]
	v_mov_b32_e32 v172, v199
	s_waitcnt lgkmcnt(0)
	s_barrier
	v_readlane_b32 s0, v253, 20
	v_bfe_u32 v170, v172, 4, 2
	v_readfirstlane_b32 s2, v172
	v_and_b32_e32 v204, 15, v172
	v_lshlrev_b32_e32 v161, 3, v170
	v_readlane_b32 s1, v253, 21
	s_ashr_i32 s14, s2, 6
	v_lshlrev_b32_e32 v205, 2, v170
	v_mul_u32_u24_e32 v141, 0x90, v204
	s_andn2_b64 vcc, exec, s[0:1]
	v_and_b32_e32 v171, 48, v172
	v_lshlrev_b32_e32 v128, 1, v161
	s_cbranch_vccnz .LBB0_882
	s_movk_i32 s0, 0x880
	s_cmp_gt_i32 s14, 3
	v_cmp_gt_i32_e64 s[4:5], s0, v172
	s_cselect_b64 s[0:1], -1, 0
	s_cmp_lt_i32 s14, 4
	s_mov_b32 s3, 0x1c800000
	s_cselect_b32 s3, 0x1a800000, s3
	s_add_u32 s6, s86, s3
	s_addc_u32 s7, s87, 0
	s_lshl_b32 s8, s14, 4
	s_and_b32 s8, s8, 48
	v_or_b32_e32 v173, s8, v204
	v_lshlrev_b32_e32 v0, 8, v173
	v_mov_b32_e32 v1, v197
	v_lshl_add_u64 v[0:1], s[6:7], 0, v[0:1]
	v_readlane_b32 s6, v253, 14
	v_and_b32_e32 v196, 63, v172
	v_lshlrev_b32_e32 v196, 4, v196
	v_lshl_or_b32 v196, s8, 7, v196
	v_mov_b32_e32 v129, v197
	v_readlane_b32 s7, v253, 15
	v_lshl_add_u64 v[130:131], v[0:1], 0, v[128:129]
	v_lshlrev_b32_e32 v2, 7, v204
	v_lshl_add_u64 v[0:1], s[6:7], 0, v[196:197]
	v_mov_b64_e32 v[132:133], v[0:1]
	v_and_b32_e32 v0, 63, v172
	v_lshlrev_b32_e32 v0, 3, v0
	v_lshl_or_b32 v0, s14, 10, v0
	v_ashrrev_i32_e32 v1, 31, v0
	v_lshlrev_b64 v[134:135], 1, v[0:1]
	v_lshl_add_u64 v[0:1], s[92:93], 0, v[134:135]
	s_movk_i32 s6, 0x110
	v_mov_b64_e32 v[136:137], v[0:1]
	v_mad_u32_u24 v0, v204, s6, 0
	v_add_u32_e32 v129, v0, v128
	s_lshl_b32 s6, s8, 1
	v_sub_u32_e32 v0, v0, v2
	s_lshl_b32 s2, s2, 5
	s_add_i32 s7, s6, 0
	v_add_u32_e32 v176, s6, v0
	v_mul_i32_i24_e32 v3, 0xffffff72, v204
	s_lshl_b32 s6, s14, 5
	s_and_b32 s2, s2, 0x1800
	v_add_u32_e32 v177, v0, v128
	v_add3_u32 v3, v0, v3, s6
	v_or_b32_e32 v0, s8, v205
	v_lshlrev_b32_e32 v5, 9, v170
	v_or_b32_e32 v2, s2, v2
	v_mul_u32_u24_e32 v1, 0x110, v204
	v_add_u32_e32 v174, 0, v128
	v_lshlrev_b32_e32 v0, 7, v0
	v_mul_u32_u24_e32 v4, 0x440, v170
	v_or3_b32 v5, s2, v5, v204
	v_and_b32_e32 v140, 63, v172
	v_lshl_or_b32 v140, v140, 4, s2
	v_lshlrev_b32_e32 v2, 1, v2
	v_add_u32_e32 v175, s7, v141
	v_add_u32_e32 v178, 0xfffffe00, v172
	v_lshl_add_u32 v179, v172, 1, 0
	v_lshlrev_b32_e32 v138, 1, v5
	v_mov_b32_e32 v139, v197
	s_nop 0
	v_or3_b32 v142, s3, v171, v2
	v_mov_b32_e32 v143, v197
	v_lshlrev_b32_e32 v144, 1, v0
	v_add_u32_e32 v180, v3, v4
	v_add_u32_e32 v181, v174, v1
	v_readlane_b32 s15, v254, 13
	s_mov_b32 s16, s46
	s_branch .LBB0_846

; __global__ void __launch_bounds__(512, 2) fwd_megakernel(Params kp_) {
;     ...
;                             bf16x8 fa1[4], fb1[2], fk1[2]; float uv1[4]; float eg1;
;                             bf16x8 fa2[4], fb2[2], fk2[2]; float uv2[4]; float eg2;
;                             GS_LOAD(fa, fb, fk, uv, eg, 0); GS_LOAD(fa1, fb1, fk1, uv1, eg1, 1);
;     ...
;                             for (int n = 0; n < 126; n += 3) {
;                                 GS_STEP(fa, fb, fk, uv, eg, fa2, fb2, fk2, uv2, eg2, n);
;                                 GS_STEP(fa1, fb1, fk1, uv1, eg1, fa, fb, fk, uv, eg, n + 1);
.LBB0_849:
	s_or_b64 exec, exec, s[2:3]
	s_lshl_b32 s3, s15, 1
	s_bfe_u32 s2, s15, 0x30001
	s_and_b32 s12, s3, 0xe0
	s_lshl_b32 s3, s16, 1
	s_lshl_b32 s8, s2, 1
	s_lshl_b32 s10, s2, 12
	s_and_b32 s2, s3, 14
	s_ashr_i32 s11, s16, 6
	s_add_i32 s2, s2, s11
	s_and_b32 s17, s3, 0x70
	s_ashr_i32 s3, s2, 31
	s_lshl_b64 s[18:19], s[2:3], 20
	s_lshl_b64 s[6:7], s[2:3], 21
	v_readlane_b32 s13, v253, 18
	v_lshl_add_u64 v[0:1], v[130:131], 0, s[6:7]
	v_lshl_add_u64 v[2:3], v[136:137], 0, s[6:7]
	s_add_u32 s6, s13, s6
	v_readlane_b32 s22, v253, 19
	s_addc_u32 s7, s22, s7
	s_lshl_b32 s9, s17, 1
	s_add_u32 s6, s6, s9
	s_waitcnt lgkmcnt(0)
	s_barrier
	global_load_dwordx4 v[60:63], v[0:1], off
	global_load_dwordx4 v[48:51], v[0:1], off offset:64
	global_load_dwordx4 v[52:55], v[0:1], off offset:128
	global_load_dwordx4 v[56:59], v[0:1], off offset:192
	v_lshl_add_u64 v[0:1], v[132:133], 0, s[18:19]
	s_addc_u32 s7, s7, 0
	v_lshlrev_b32_e32 v196, 1, v204
	global_load_dwordx4 v[40:43], v[0:1], off
	global_load_dwordx4 v[8:11], v[2:3], off
	global_load_dwordx4 v[44:47], v[0:1], off offset:1024
	global_load_dwordx4 v[12:15], v[2:3], off offset:1024
	v_lshl_add_u64 v[0:1], s[6:7], 0, v[196:197]
	v_mov_b32_e32 v145, v197
	v_lshl_add_u64 v[0:1], v[0:1], 0, v[144:145]
	global_load_ushort v2, v[0:1], off
	global_load_ushort v3, v[0:1], off offset:256
	s_lshl_b64 s[6:7], s[2:3], 9
	v_readlane_b32 s3, v253, 10
	s_add_u32 s6, s3, s6
	v_readlane_b32 s3, v253, 11
	s_addc_u32 s7, s3, s7
	s_bitset1_b32 s18, 13
	s_lshl_b64 s[20:21], s[18:19], 1
	s_add_u32 s3, s13, s20
	s_addc_u32 s13, s22, s21
	v_lshl_add_u64 v[4:5], v[132:133], 0, s[18:19]
	s_add_u32 s18, s3, s9
	s_addc_u32 s19, s13, 0
	v_lshl_add_u64 v[6:7], v[136:137], 0, s[20:21]
	s_waitcnt vmcnt(14)
	v_lshl_add_u64 v[64:65], s[18:19], 0, v[196:197]
	v_lshl_add_u64 v[66:67], v[64:65], 0, v[144:145]
	s_lshl_b32 s3, s2, 7
	s_and_b32 s18, s3, 0x180
	s_lshl_b32 s3, s18, 1
	v_lshlrev_b32_e32 v196, 1, v205
	v_mov_b32_e32 v80, 0
	v_mov_b32_e32 v81, v80
	v_mov_b32_e32 v82, v80
	v_mov_b32_e32 v83, v80
	s_waitcnt vmcnt(1)
	v_lshlrev_b32_e32 v68, 16, v2
	global_load_ushort v2, v[0:1], off offset:512
	s_nop 0
	global_load_ushort v0, v[0:1], off offset:768
	s_waitcnt vmcnt(2)
	v_lshlrev_b32_e32 v69, 16, v3
	s_waitcnt vmcnt(1)
	v_lshlrev_b32_e32 v70, 16, v2
	s_waitcnt vmcnt(0)
	v_lshlrev_b32_e32 v71, 16, v0
	v_lshl_add_u64 v[0:1], v[130:131], 0, s[20:21]
	global_load_dwordx4 v[24:27], v[0:1], off
	global_load_dwordx4 v[28:31], v[0:1], off offset:64
	global_load_dwordx4 v[32:35], v[0:1], off offset:128
	global_load_dwordx4 v[36:39], v[0:1], off offset:192
	global_load_dwordx4 v[20:23], v[4:5], off
	s_nop 0
	global_load_dwordx4 v[0:3], v[6:7], off
	global_load_dwordx4 v[16:19], v[4:5], off offset:1024
	s_nop 0
	global_load_dwordx4 v[4:7], v[6:7], off offset:1024
	s_nop 0
	global_load_ushort v64, v[66:67], off
	global_load_ushort v65, v[66:67], off offset:256
	global_load_ushort v72, v[66:67], off offset:512
	s_nop 0
	global_load_ushort v66, v[66:67], off offset:768
	s_waitcnt vmcnt(3)
	v_lshlrev_b32_e32 v64, 16, v64
	global_load_dwordx2 v[146:147], v197, s[6:7]
	v_readlane_b32 s6, v253, 53
	v_readlane_b32 s7, v253, 54
	s_add_u32 s3, s6, s3
	s_addc_u32 s7, s7, 0
	s_add_u32 s6, s3, s9
	s_addc_u32 s7, s7, 0
	v_lshl_add_u64 v[148:149], s[6:7], 0, v[196:197]
	s_add_i32 s6, s11, s8
	s_ashr_i32 s7, s6, 31
	s_lshl_b32 s3, s11, 11
	s_lshl_b64 s[20:21], s[6:7], 21
	s_add_i32 s10, s10, s3
	s_lshl_b64 s[8:9], s[6:7], 9
	s_or_b32 s12, s20, s12
	s_mov_b32 s13, s21
	s_lshl_b64 s[6:7], s[6:7], 20
	s_and_b32 s3, s10, 0xffffe000
	s_waitcnt vmcnt(3)
	v_lshlrev_b32_e32 v65, 16, v65
	s_waitcnt vmcnt(1)
	v_lshlrev_b32_e32 v67, 16, v66
	v_lshlrev_b32_e32 v66, 16, v72
	v_lshl_add_u64 v[150:151], s[12:13], 0, v[138:139]
	v_lshl_add_u64 v[152:153], v[134:135], 0, s[20:21]
	v_mov_b32_e32 v155, s7
	v_or_b32_e32 v154, s6, v140
	v_lshl_add_u64 v[156:157], v[142:143], 0, s[20:21]
	v_or_b32_e32 v158, s3, v173
	s_mov_b32 s3, -3
.LBB0_850:
	v_lshl_add_u64 v[168:169], s[86:87], 0, v[156:157]
	s_mov_b32 s6, 0x8000
	v_add_co_u32_e32 v72, vcc, s6, v168
	v_lshl_add_u64 v[166:167], s[86:87], 0, v[154:155]
	s_nop 0
	v_addc_co_u32_e32 v73, vcc, 0, v169, vcc
	s_mov_b32 s6, 0x4804000
	global_load_dwordx4 v[92:95], v[72:73], off
	global_load_dwordx4 v[96:99], v[72:73], off offset:64
	global_load_dwordx4 v[100:103], v[72:73], off offset:128
	global_load_dwordx4 v[104:107], v[72:73], off offset:192
	v_add_co_u32_e32 v72, vcc, s6, v166
	v_lshl_add_u64 v[162:163], s[86:87], 0, v[152:153]
	s_nop 0
	v_addc_co_u32_e32 v73, vcc, 0, v167, vcc
	s_mov_b32 s6, 0x2808000
	v_add_co_u32_e32 v74, vcc, s6, v162
	v_lshl_add_u64 v[164:165], s[86:87], 0, v[150:151]
	s_nop 0
	v_addc_co_u32_e32 v75, vcc, 0, v163, vcc
	s_mov_b32 s6, 0x18808000
	v_add_co_u32_e32 v108, vcc, s6, v164
	s_add_u32 s10, s86, s8
	s_nop 0
	v_addc_co_u32_e32 v109, vcc, 0, v165, vcc
	global_load_dwordx4 v[88:91], v[72:73], off
	global_load_dwordx4 v[84:87], v[72:73], off offset:1024
	global_load_dwordx4 v[76:79], v[74:75], off
	s_nop 0
	global_load_dwordx4 v[72:75], v[74:75], off offset:1024
	s_addc_u32 s11, s87, s9
	global_load_ushort v145, v[108:109], off
	global_load_ushort v182, v[108:109], off offset:256
	global_load_ushort v183, v[108:109], off offset:512
	global_load_ushort v184, v[108:109], off offset:768
	global_load_dword v160, v239, s[10:11] offset:8
	ds_read_b128 v[108:111], v129
	ds_read_b128 v[112:115], v129 offset:64
	ds_read_b128 v[116:119], v129 offset:128
	ds_read_b128 v[120:123], v129 offset:192
	v_cndmask_b32_e64 v124, 0, 1, s[0:1]
	v_cmp_ne_u32_e64 s[6:7], 1, v124
	s_andn2_b64 vcc, exec, s[0:1]
	s_mov_b64 s[12:13], -1
	s_cbranch_vccnz .LBB0_852
	s_waitcnt lgkmcnt(3)
	v_mfma_f32_16x16x32_bf16 v[124:127], v[108:111], v[60:63], 0
	s_mov_b64 s[12:13], 0
	s_waitcnt lgkmcnt(2)
	v_mfma_f32_16x16x32_bf16 v[124:127], v[112:115], v[48:51], v[124:127]
	s_waitcnt lgkmcnt(1)
	v_mfma_f32_16x16x32_bf16 v[124:127], v[116:119], v[52:55], v[124:127]
	s_waitcnt lgkmcnt(0)
	v_mfma_f32_16x16x32_bf16 v[124:127], v[120:123], v[56:59], v[124:127]

.LBB0_856:
	s_waitcnt vmcnt(13)
	v_pk_mul_f32 v[42:43], v[82:83], v[146:147] op_sel_hi:[1,0]
	v_pk_mul_f32 v[40:41], v[80:81], v[146:147] op_sel_hi:[1,0]
	s_mov_b32 s12, 0xc000
	v_add_co_u32_e32 v60, vcc, s12, v168
	s_waitcnt lgkmcnt(1)
	v_mfma_f32_16x16x32_bf16 v[8:11], v[48:51], v[8:11], v[40:43]
	v_addc_co_u32_e32 v61, vcc, 0, v169, vcc
	s_mov_b32 s12, 0x4806000
	s_waitcnt lgkmcnt(0)
	v_mfma_f32_16x16x32_bf16 v[68:71], v[52:55], v[12:15], v[8:11]
	v_add_co_u32_e32 v12, vcc, s12, v166
	s_mov_b32 s12, 0x280c000
	s_nop 0
	v_addc_co_u32_e32 v13, vcc, 0, v167, vcc
	v_add_co_u32_e32 v14, vcc, s12, v162
	s_nop 2
	v_cvt_pk_bf16_f32 v8, v68, s0
	v_addc_co_u32_e32 v15, vcc, 0, v163, vcc
	s_mov_b32 s12, 0x1880c000
	v_cvt_pk_bf16_f32 v9, v69, s0
	v_cvt_pk_bf16_f32 v10, v70, s0
	v_cvt_pk_bf16_f32 v11, v71, s0
	ds_write_b16 v180, v8
	ds_write_b16 v180, v9 offset:272
	ds_write_b16 v180, v10 offset:544
	ds_write_b16 v180, v11 offset:816
	v_add_co_u32_e32 v62, vcc, s12, v164
	s_waitcnt lgkmcnt(0)
	s_barrier
	global_load_dwordx4 v[48:51], v[60:61], off offset:64
	global_load_dwordx4 v[52:55], v[60:61], off offset:128
	v_addc_co_u32_e32 v63, vcc, 0, v165, vcc
	global_load_dwordx4 v[56:59], v[60:61], off offset:192
	global_load_dwordx4 v[40:43], v[12:13], off
	global_load_dwordx4 v[8:11], v[14:15], off
	global_load_dwordx4 v[44:47], v[12:13], off offset:1024
	s_nop 0
	global_load_dwordx4 v[12:15], v[14:15], off offset:1024
	s_nop 0
	global_load_ushort v125, v[62:63], off
	global_load_ushort v159, v[62:63], off offset:256
	global_load_ushort v126, v[62:63], off offset:512
	global_load_ushort v127, v[62:63], off offset:768
	s_nop 0
	global_load_dwordx4 v[60:63], v[60:61], off
	s_nop 0
	global_load_dword v124, v239, s[10:11] offset:12
	ds_read_b128 v[80:83], v181
	ds_read_b128 v[108:111], v181 offset:64
	ds_read_b128 v[112:115], v181 offset:128
	ds_read_b128 v[116:119], v181 offset:192
	s_and_b64 vcc, exec, s[6:7]
	s_mov_b64 s[12:13], -1
	s_cbranch_vccnz .LBB0_858
	s_waitcnt lgkmcnt(3)
	v_mfma_f32_16x16x32_bf16 v[120:123], v[80:83], v[24:27], 0
	s_mov_b64 s[12:13], 0
	s_waitcnt lgkmcnt(2)
	v_mfma_f32_16x16x32_bf16 v[120:123], v[108:111], v[28:31], v[120:123]
	s_waitcnt lgkmcnt(1)
	v_mfma_f32_16x16x32_bf16 v[120:123], v[112:115], v[32:35], v[120:123]
	s_waitcnt lgkmcnt(0)
	v_mfma_f32_16x16x32_bf16 v[120:123], v[116:119], v[36:39], v[120:123]

.LBB0_862:
	v_pk_mul_f32 v[16:17], v[146:147], v[68:69] op_sel:[1,0]
	v_pk_mul_f32 v[18:19], v[146:147], v[70:71] op_sel:[1,0]
	s_mov_b32 s12, 0x10000
	s_waitcnt lgkmcnt(1)
	v_mfma_f32_16x16x32_bf16 v[0:3], v[24:27], v[0:3], v[16:19]
	s_waitcnt lgkmcnt(0)
	v_mfma_f32_16x16x32_bf16 v[80:83], v[28:31], v[4:7], v[0:3]
	s_nop 7
	v_cvt_pk_bf16_f32 v0, v80, s0
	v_cvt_pk_bf16_f32 v1, v81, s0
	v_cvt_pk_bf16_f32 v2, v82, s0
	v_cvt_pk_bf16_f32 v3, v83, s0
	ds_write_b16 v180, v0
	ds_write_b16 v180, v1 offset:272
	ds_write_b16 v180, v2 offset:544
	ds_write_b16 v180, v3 offset:816
	v_add_co_u32_e32 v0, vcc, s12, v168
	s_waitcnt lgkmcnt(0)
	s_barrier
	s_mov_b32 s12, 0x4808000
	s_nop 0
	v_addc_co_u32_e32 v1, vcc, 0, v169, vcc
	global_load_dwordx4 v[24:27], v[0:1], off
	global_load_dwordx4 v[28:31], v[0:1], off offset:64
	global_load_dwordx4 v[32:35], v[0:1], off offset:128
	global_load_dwordx4 v[36:39], v[0:1], off offset:192
	v_add_co_u32_e32 v0, vcc, s12, v166
	s_mov_b32 s12, 0x2810000
	s_nop 0
	v_addc_co_u32_e32 v1, vcc, 0, v167, vcc
	v_add_co_u32_e32 v4, vcc, s12, v162
	s_nop 1
	v_addc_co_u32_e32 v5, vcc, 0, v163, vcc
	v_add_co_u32_e32 v64, vcc, 0x18810000, v164
	global_load_dwordx4 v[20:23], v[0:1], off
	global_load_dwordx4 v[16:19], v[0:1], off offset:1024
	s_nop 0
	global_load_dwordx4 v[0:3], v[4:5], off
	s_nop 0
	global_load_dwordx4 v[4:7], v[4:5], off offset:1024
	v_addc_co_u32_e32 v65, vcc, 0, v165, vcc
	global_load_ushort v122, v[64:65], off
	global_load_ushort v123, v[64:65], off offset:256
	global_load_ushort v120, v[64:65], off offset:512
	global_load_ushort v121, v[64:65], off offset:768
	global_load_dword v147, v239, s[10:11] offset:16
	ds_read_b128 v[64:67], v181
	ds_read_b128 v[68:71], v181 offset:64
	ds_read_b128 v[108:111], v181 offset:128
	ds_read_b128 v[112:115], v181 offset:192
	s_and_b64 vcc, exec, s[6:7]
	s_mov_b64 s[10:11], -1
	s_cbranch_vccnz .LBB0_864
	s_waitcnt vmcnt(38) lgkmcnt(3)
	v_mfma_f32_16x16x32_bf16 v[116:119], v[64:67], v[92:95], 0
	s_mov_b64 s[10:11], 0
	s_waitcnt vmcnt(37) lgkmcnt(2)
	v_mfma_f32_16x16x32_bf16 v[116:119], v[68:71], v[96:99], v[116:119]
	s_waitcnt vmcnt(36) lgkmcnt(1)
	v_mfma_f32_16x16x32_bf16 v[116:119], v[108:111], v[100:103], v[116:119]
	s_waitcnt vmcnt(35) lgkmcnt(0)
	v_mfma_f32_16x16x32_bf16 v[116:119], v[112:115], v[104:107], v[116:119]

; __device__ __forceinline__ float shfl_idx(float v, int src_lane) { return __builtin_bit_cast(float, __builtin_amdgcn_ds_bpermute(src_lane << 2, __builtin_bit_cast(int, v))); }
;     __device__ __forceinline__ void operator()(f32x4 (&acc)[2][2][4][2], const Unit& u, int wr, int wc, int fr, int fq) const {
;         const int row0 = u.pm * BM + wr * 64 + fr, col0 = u.pn * BM + wc * 32 + 8 * fq, b = (u.pm * BM) >> 13, lane = fr + 16 * fq, tid = (wr * 4 + wc) * 64 + lane;
;         const float* gp = gate + (size_t)b * 6144 + col0;
;         f32x4 gv[2][2];
; #pragma unroll
;         for (int bj = 0; bj < 2; ++bj)
; #pragma unroll
;             for (int n = 0; n < 2; ++n) gv[bj][n] = *(const f32x4*)(gp + bj * HALF + 4 * n);
; #pragma unroll
;         for (int ai = 0; ai < 2; ++ai)
; #pragma unroll
;             for (int m = 0; m < 4; ++m) { const size_t ro = (size_t)(row0 + ai * HALF + m * 16) * 1024 + col0; float ss = 0.f;
; #pragma unroll
;                 for (int bj = 0; bj < 2; ++bj)
; #pragma unroll
;                     for (int n = 0; n < 2; ++n) { const f32x4 xv = *(const f32x4*)(xin + ro + bj * HALF + 4 * n); const f32x4 x = xv + gv[bj][n] * acc[ai][bj][m][n];
;                         *(f32x4*)(out + ro + bj * HALF + 4 * n) = x; acc[ai][bj][m][n] = x; ss += (x.x * x.x + x.y * x.y) + (x.z * x.z + x.w * x.w); }
;                 if (donorm) { ss += shfl_idx(ss, lane ^ 16); ss += shfl_idx(ss, lane ^ 32); if (fq == 0) lp[(ai * HALF + wr * 64 + m * 16 + fr) * 4 + wc] = ss; }
.LBB0_1024:
	v_and_b32_e32 v168, 63, v199
	v_bfe_u32 v169, v199, 4, 2
	v_lshlrev_b32_e32 v169, 2, v169
	v_xor_b32_e32 v169, v168, v169
	v_and_b32_e32 v170, 0x1c0, v199
	v_add_u32_e32 v173, 64, v170
	v_and_b32_e32 v173, 0x200, v173
	v_lshl_add_u32 v170, v170, 4, v173
	v_bfe_u32 v173, v199, 8, 1
	v_mul_u32_u24_e32 v173, 0x1400, v173
	v_add_u32_e32 v170, v170, v173
	v_add_u32_e32 v170, 0x20000, v170
	v_lshl_add_u32 v174, v169, 4, v170
	v_lshrrev_b32_e32 v171, 2, v168
	v_and_b32_e32 v172, 3, v168
	v_lshlrev_b32_e32 v173, 2, v172
	v_xor_b32_e32 v171, v171, v173
	v_lshl_or_b32 v171, v172, 4, v171
	v_lshl_add_u32 v175, v171, 4, v170
	ds_write_b128 v174, v[0:3]
	ds_read_b128 v[0:3], v175
	ds_write_b128 v174, v[4:7]
	ds_read_b128 v[4:7], v175
	ds_write_b128 v174, v[8:11]
	ds_read_b128 v[8:11], v175
	ds_write_b128 v174, v[12:15]
	ds_read_b128 v[12:15], v175
	ds_write_b128 v174, v[16:19]
	ds_read_b128 v[16:19], v175
	ds_write_b128 v174, v[20:23]
	ds_read_b128 v[20:23], v175
	ds_write_b128 v174, v[24:27]
	ds_read_b128 v[24:27], v175
	ds_write_b128 v174, v[28:31]
	ds_read_b128 v[28:31], v175
	ds_write_b128 v174, v[32:35]
	ds_read_b128 v[32:35], v175
	ds_write_b128 v174, v[36:39]
	ds_read_b128 v[36:39], v175
	ds_write_b128 v174, v[40:43]
	ds_read_b128 v[40:43], v175
	ds_write_b128 v174, v[44:47]
	ds_read_b128 v[44:47], v175
	ds_write_b128 v174, v[48:51]
	ds_read_b128 v[48:51], v175
	ds_write_b128 v174, v[52:55]
	ds_read_b128 v[52:55], v175
	ds_write_b128 v174, v[56:59]
	ds_read_b128 v[56:59], v175
	ds_write_b128 v174, v[60:63]
	ds_read_b128 v[60:63], v175
	ds_write_b128 v174, v[64:67]
	ds_read_b128 v[64:67], v175
	ds_write_b128 v174, v[68:71]
	ds_read_b128 v[68:71], v175
	ds_write_b128 v174, v[72:75]
	ds_read_b128 v[72:75], v175
	ds_write_b128 v174, v[76:79]
	ds_read_b128 v[76:79], v175
	ds_write_b128 v174, v[80:83]
	ds_read_b128 v[80:83], v175
	ds_write_b128 v174, v[84:87]
	ds_read_b128 v[84:87], v175
	ds_write_b128 v174, v[88:91]
	ds_read_b128 v[88:91], v175
	ds_write_b128 v174, v[92:95]
	ds_read_b128 v[92:95], v175
	ds_write_b128 v174, v[96:99]
	ds_read_b128 v[96:99], v175
	ds_write_b128 v174, v[100:103]
	ds_read_b128 v[100:103], v175
	ds_write_b128 v174, v[104:107]
	ds_read_b128 v[104:107], v175
	ds_write_b128 v174, v[108:111]
	ds_read_b128 v[108:111], v175
	ds_write_b128 v174, v[112:115]
	ds_read_b128 v[112:115], v175
	ds_write_b128 v174, v[116:119]
	ds_read_b128 v[116:119], v175
	ds_write_b128 v174, v[120:123]
	ds_read_b128 v[120:123], v175
	ds_write_b128 v174, v[124:127]
	ds_read_b128 v[124:127], v175
	s_waitcnt lgkmcnt(0)
	s_lshl_b32 s0, s18, 8
	v_mov_b32_e32 v154, v199
	s_add_i32 s13, s0, s34
	s_lshl_b32 s0, s20, 8
	s_or_b32 s0, s0, s35
	v_bfe_u32 v214, v154, 2, 4
	v_and_b32_e32 v155, 3, v154
	v_lshl_or_b32 v188, v155, 3, s0
	s_ashr_i32 s0, s18, 5
	v_or_b32_e32 v190, s13, v214
	s_mul_hi_i32 s1, s0, 0x1800
	s_mulk_i32 s0, 0x1800
	v_ashrrev_i32_e32 v191, 31, v190
	s_lshl_b64 s[8:9], s[0:1], 2
	v_readlane_b32 s0, v255, 16
	v_ashrrev_i32_e32 v189, 31, v188
	v_lshlrev_b64 v[128:129], 10, v[190:191]
	s_add_u32 s0, s0, s8
	v_readlane_b32 s1, v255, 17
	v_lshl_add_u64 v[128:129], v[128:129], 0, v[188:189]
	s_addc_u32 s1, s1, s9
	v_lshlrev_b64 v[148:149], 2, v[128:129]
	v_lshl_add_u64 v[132:133], v[188:189], 2, s[0:1]
	v_lshl_add_u64 v[150:151], s[62:63], 0, v[148:149]
	global_load_dwordx4 v[144:147], v[150:151], off
	global_load_dwordx4 v[160:163], v[150:151], off offset:16
	global_load_dwordx4 v[164:167], v[150:151], off offset:512
	global_load_dwordx4 v[168:171], v[150:151], off offset:528
	global_load_dwordx4 v[140:143], v[132:133], off
	global_load_dwordx4 v[136:139], v[132:133], off offset:16
	global_load_dwordx4 v[128:131], v[132:133], off offset:528
	s_nop 0
	global_load_dwordx4 v[132:135], v[132:133], off offset:512
	v_lshl_add_u64 v[152:153], s[84:85], 0, v[148:149]
	v_cmp_eq_u32_e32 vcc, 0, v155
	s_waitcnt vmcnt(0)
	v_pk_fma_f32 v[54:55], v[54:55], v[142:143], v[146:147]
	v_pk_fma_f32 v[52:53], v[52:53], v[140:141], v[144:145]
	global_store_dwordx4 v[152:153], v[52:55], off
	s_waitcnt vmcnt(1)
	v_pk_fma_f32 v[58:59], v[58:59], v[138:139], v[162:163]
	v_pk_fma_f32 v[56:57], v[56:57], v[136:137], v[160:161]
	global_store_dwordx4 v[152:153], v[56:59], off offset:16
	v_mul_f32_e32 v156, v59, v59
	v_fmac_f32_e32 v156, v58, v58
	s_waitcnt vmcnt(2)
	v_pk_fma_f32 v[66:67], v[66:67], v[134:135], v[166:167]
	v_pk_fma_f32 v[64:65], v[64:65], v[132:133], v[164:165]
	global_store_dwordx4 v[152:153], v[64:67], off offset:512
	v_and_b32_e32 v144, 63, v154
	v_mul_f32_e32 v151, v53, v53
	v_mul_f32_e32 v154, v55, v55
	v_fmac_f32_e32 v151, v52, v52
	v_fmac_f32_e32 v154, v54, v54
	v_add_f32_e32 v151, v151, v154
	v_mul_f32_e32 v154, v57, v57
	v_fmac_f32_e32 v154, v56, v56
	v_add_f32_e32 v154, v154, v156
	v_add_f32_e32 v151, v151, v154
	v_mul_f32_e32 v154, v65, v65
	v_mul_f32_e32 v156, v67, v67
	v_fmac_f32_e32 v154, v64, v64
	v_fmac_f32_e32 v156, v66, v66
	v_add_f32_e32 v154, v154, v156
	v_lshlrev_b32_e32 v150, 2, v144
	v_add_f32_e32 v151, v151, v154
	v_xor_b32_e32 v145, 4, v150
	s_waitcnt vmcnt(3)
	v_pk_fma_f32 v[74:75], v[74:75], v[130:131], v[170:171]
	v_pk_fma_f32 v[72:73], v[72:73], v[128:129], v[168:169]
	v_mul_f32_e32 v147, v75, v75
	v_mul_f32_e32 v146, v73, v73
	v_fmac_f32_e32 v146, v72, v72
	v_fmac_f32_e32 v147, v74, v74
	v_add_f32_e32 v146, v146, v147
	v_add_f32_e32 v146, v151, v146
	ds_bpermute_b32 v148, v145, v146
	v_xor_b32_e32 v147, 8, v150
	global_store_dwordx4 v[152:153], v[72:75], off offset:528
	s_waitcnt lgkmcnt(0)
	v_add_f32_e32 v148, v146, v148
	ds_bpermute_b32 v149, v147, v148
	v_or_b32_e32 v146, s34, v214
	s_and_saveexec_b64 s[0:1], vcc
	s_cbranch_execz .LBB0_1026
	v_lshl_add_u32 v150, v146, 4, s39
	s_waitcnt lgkmcnt(0)
	v_add_f32_e32 v148, v148, v149
	ds_write_b32 v150, v148
; __device__ __forceinline__ float shfl_idx(float v, int src_lane) { return __builtin_bit_cast(float, __builtin_amdgcn_ds_bpermute(src_lane << 2, __builtin_bit_cast(int, v))); }
;     __device__ __forceinline__ void operator()(f32x4 (&acc)[2][2][4][2], const Unit& u, int wr, int wc, int fr, int fq) const {
;     ...
;             for (int m = 0; m < 4; ++m) { const size_t ro = (size_t)(row0 + ai * HALF + m * 16) * 1024 + col0; float ss = 0.f;
; #pragma unroll
;                 for (int bj = 0; bj < 2; ++bj)
; #pragma unroll
;                     for (int n = 0; n < 2; ++n) { const f32x4 xv = *(const f32x4*)(xin + ro + bj * HALF + 4 * n); const f32x4 x = xv + gv[bj][n] * acc[ai][bj][m][n];
;                         *(f32x4*)(out + ro + bj * HALF + 4 * n) = x; acc[ai][bj][m][n] = x; ss += (x.x * x.x + x.y * x.y) + (x.z * x.z + x.w * x.w); }
;                 if (donorm) { ss += shfl_idx(ss, lane ^ 16); ss += shfl_idx(ss, lane ^ 32); if (fq == 0) lp[(ai * HALF + wr * 64 + m * 16 + fr) * 4 + wc] = ss; }
.LBB0_1026:
	s_or_b64 exec, exec, s[0:1]
	v_or_b32_e32 v194, 16, v190
	v_ashrrev_i32_e32 v195, 31, v194
	s_waitcnt lgkmcnt(0)
	v_lshlrev_b64 v[148:149], 10, v[194:195]
	v_lshl_add_u64 v[148:149], v[148:149], 0, v[188:189]
	v_lshlrev_b64 v[152:153], 2, v[148:149]
	v_lshl_add_u64 v[154:155], s[62:63], 0, v[152:153]
	global_load_dwordx4 v[148:151], v[154:155], off
	global_load_dwordx4 v[160:163], v[154:155], off offset:16
	global_load_dwordx4 v[164:167], v[154:155], off offset:512
	global_load_dwordx4 v[168:171], v[154:155], off offset:528
	v_lshl_add_u64 v[152:153], s[84:85], 0, v[152:153]
	s_waitcnt vmcnt(3)
	v_pk_fma_f32 v[86:87], v[86:87], v[142:143], v[150:151]
	v_pk_fma_f32 v[84:85], v[84:85], v[140:141], v[148:149]
	global_store_dwordx4 v[152:153], v[84:87], off
	s_waitcnt vmcnt(3)
	v_pk_fma_f32 v[94:95], v[94:95], v[138:139], v[162:163]
	v_pk_fma_f32 v[92:93], v[92:93], v[136:137], v[160:161]
	global_store_dwordx4 v[152:153], v[92:95], off offset:16
	v_mul_f32_e32 v156, v95, v95
	v_fmac_f32_e32 v156, v94, v94
	s_waitcnt vmcnt(3)
	v_pk_fma_f32 v[82:83], v[82:83], v[134:135], v[166:167]
	v_pk_fma_f32 v[80:81], v[80:81], v[132:133], v[164:165]
	global_store_dwordx4 v[152:153], v[80:83], off offset:512
	v_mul_f32_e32 v154, v85, v85
	v_mul_f32_e32 v155, v87, v87
	v_fmac_f32_e32 v154, v84, v84
	v_fmac_f32_e32 v155, v86, v86
	v_add_f32_e32 v154, v154, v155
	v_mul_f32_e32 v155, v93, v93
	v_fmac_f32_e32 v155, v92, v92
	v_add_f32_e32 v155, v155, v156
	v_add_f32_e32 v154, v154, v155
	v_mul_f32_e32 v155, v81, v81
	v_mul_f32_e32 v156, v83, v83
	v_fmac_f32_e32 v155, v80, v80
	v_fmac_f32_e32 v156, v82, v82
	v_add_f32_e32 v155, v155, v156
	v_add_f32_e32 v154, v154, v155
	s_waitcnt vmcnt(3)
	v_pk_fma_f32 v[98:99], v[98:99], v[130:131], v[170:171]
	v_pk_fma_f32 v[96:97], v[96:97], v[128:129], v[168:169]
	v_mul_f32_e32 v149, v99, v99
	v_mul_f32_e32 v148, v97, v97
	v_fmac_f32_e32 v148, v96, v96
	v_fmac_f32_e32 v149, v98, v98
	v_add_f32_e32 v148, v148, v149
	v_add_f32_e32 v148, v154, v148
	ds_bpermute_b32 v149, v145, v148
	global_store_dwordx4 v[152:153], v[96:99], off offset:528
	s_waitcnt lgkmcnt(0)
	v_add_f32_e32 v148, v148, v149
	ds_bpermute_b32 v149, v147, v148
	s_and_saveexec_b64 s[0:1], vcc
	s_cbranch_execz .LBB0_1028
	v_lshl_add_u32 v150, v146, 4, s39
	s_waitcnt lgkmcnt(0)
	v_add_f32_e32 v148, v148, v149
	ds_write_b32 v150, v148 offset:256
.LBB0_1028:
	s_or_b64 exec, exec, s[0:1]
	v_or_b32_e32 v186, 32, v190
	v_ashrrev_i32_e32 v187, 31, v186
	s_waitcnt lgkmcnt(0)
	v_lshlrev_b64 v[148:149], 10, v[186:187]
	v_lshl_add_u64 v[148:149], v[148:149], 0, v[188:189]
	v_lshlrev_b64 v[152:153], 2, v[148:149]
	v_lshl_add_u64 v[154:155], s[62:63], 0, v[152:153]
	global_load_dwordx4 v[148:151], v[154:155], off
	global_load_dwordx4 v[160:163], v[154:155], off offset:16
	global_load_dwordx4 v[164:167], v[154:155], off offset:512
	global_load_dwordx4 v[168:171], v[154:155], off offset:528
	v_lshl_add_u64 v[152:153], s[84:85], 0, v[152:153]
	s_waitcnt vmcnt(3)
	v_pk_fma_f32 v[102:103], v[102:103], v[142:143], v[150:151]
	v_pk_fma_f32 v[100:101], v[100:101], v[140:141], v[148:149]
	global_store_dwordx4 v[152:153], v[100:103], off
	s_waitcnt vmcnt(3)
	v_pk_fma_f32 v[106:107], v[106:107], v[138:139], v[162:163]
	v_pk_fma_f32 v[104:105], v[104:105], v[136:137], v[160:161]
	global_store_dwordx4 v[152:153], v[104:107], off offset:16
	v_mul_f32_e32 v156, v107, v107
	v_fmac_f32_e32 v156, v106, v106
	s_waitcnt vmcnt(3)
	v_pk_fma_f32 v[110:111], v[110:111], v[134:135], v[166:167]
	v_pk_fma_f32 v[108:109], v[108:109], v[132:133], v[164:165]
	global_store_dwordx4 v[152:153], v[108:111], off offset:512
	v_mul_f32_e32 v154, v101, v101
	v_mul_f32_e32 v155, v103, v103
	v_fmac_f32_e32 v154, v100, v100
	v_fmac_f32_e32 v155, v102, v102
	v_add_f32_e32 v154, v154, v155
	v_mul_f32_e32 v155, v105, v105
	v_fmac_f32_e32 v155, v104, v104
	v_add_f32_e32 v155, v155, v156
	v_add_f32_e32 v154, v154, v155
	v_mul_f32_e32 v155, v109, v109
	v_mul_f32_e32 v156, v111, v111
	v_fmac_f32_e32 v155, v108, v108
	v_fmac_f32_e32 v156, v110, v110
	v_add_f32_e32 v155, v155, v156
	v_add_f32_e32 v154, v154, v155
	s_waitcnt vmcnt(3)
	v_pk_fma_f32 v[118:119], v[118:119], v[130:131], v[170:171]
	v_pk_fma_f32 v[116:117], v[116:117], v[128:129], v[168:169]
	v_mul_f32_e32 v149, v119, v119
	v_mul_f32_e32 v148, v117, v117
	v_fmac_f32_e32 v148, v116, v116
	v_fmac_f32_e32 v149, v118, v118
	v_add_f32_e32 v148, v148, v149
	v_add_f32_e32 v148, v154, v148
	ds_bpermute_b32 v149, v145, v148
	global_store_dwordx4 v[152:153], v[116:119], off offset:528
	s_waitcnt lgkmcnt(0)
	v_add_f32_e32 v148, v148, v149
	ds_bpermute_b32 v149, v147, v148
	s_and_saveexec_b64 s[0:1], vcc
	s_cbranch_execz .LBB0_1030
	v_lshl_add_u32 v150, v146, 4, s39
	s_waitcnt lgkmcnt(0)
	v_add_f32_e32 v148, v148, v149
	ds_write_b32 v150, v148 offset:512
; __device__ __forceinline__ float shfl_idx(float v, int src_lane) { return __builtin_bit_cast(float, __builtin_amdgcn_ds_bpermute(src_lane << 2, __builtin_bit_cast(int, v))); }
;     __device__ __forceinline__ void operator()(f32x4 (&acc)[2][2][4][2], const Unit& u, int wr, int wc, int fr, int fq) const {
;     ...
;             for (int m = 0; m < 4; ++m) { const size_t ro = (size_t)(row0 + ai * HALF + m * 16) * 1024 + col0; float ss = 0.f;
; #pragma unroll
;                 for (int bj = 0; bj < 2; ++bj)
; #pragma unroll
;                     for (int n = 0; n < 2; ++n) { const f32x4 xv = *(const f32x4*)(xin + ro + bj * HALF + 4 * n); const f32x4 x = xv + gv[bj][n] * acc[ai][bj][m][n];
;                         *(f32x4*)(out + ro + bj * HALF + 4 * n) = x; acc[ai][bj][m][n] = x; ss += (x.x * x.x + x.y * x.y) + (x.z * x.z + x.w * x.w); }
;                 if (donorm) { ss += shfl_idx(ss, lane ^ 16); ss += shfl_idx(ss, lane ^ 32); if (fq == 0) lp[(ai * HALF + wr * 64 + m * 16 + fr) * 4 + wc] = ss; }
.LBB0_1030:
	s_or_b64 exec, exec, s[0:1]
	v_or_b32_e32 v192, 48, v190
	v_ashrrev_i32_e32 v193, 31, v192
	s_waitcnt lgkmcnt(0)
	v_lshlrev_b64 v[148:149], 10, v[192:193]
	v_lshl_add_u64 v[148:149], v[148:149], 0, v[188:189]
	v_lshlrev_b64 v[152:153], 2, v[148:149]
	v_lshl_add_u64 v[154:155], s[62:63], 0, v[152:153]
	global_load_dwordx4 v[148:151], v[154:155], off
	global_load_dwordx4 v[160:163], v[154:155], off offset:16
	global_load_dwordx4 v[164:167], v[154:155], off offset:512
	global_load_dwordx4 v[168:171], v[154:155], off offset:528
	v_lshl_add_u64 v[152:153], s[84:85], 0, v[152:153]
	s_waitcnt vmcnt(3)
	v_pk_fma_f32 v[126:127], v[126:127], v[142:143], v[150:151]
	v_pk_fma_f32 v[124:125], v[124:125], v[140:141], v[148:149]
	global_store_dwordx4 v[152:153], v[124:127], off
	s_waitcnt vmcnt(3)
	v_pk_fma_f32 v[122:123], v[122:123], v[138:139], v[162:163]
	v_pk_fma_f32 v[120:121], v[120:121], v[136:137], v[160:161]
	global_store_dwordx4 v[152:153], v[120:123], off offset:16
	v_mul_f32_e32 v156, v123, v123
	v_fmac_f32_e32 v156, v122, v122
	s_waitcnt vmcnt(3)
	v_pk_fma_f32 v[114:115], v[114:115], v[134:135], v[166:167]
	v_pk_fma_f32 v[112:113], v[112:113], v[132:133], v[164:165]
	global_store_dwordx4 v[152:153], v[112:115], off offset:512
	v_mul_f32_e32 v154, v125, v125
	v_mul_f32_e32 v155, v127, v127
	v_fmac_f32_e32 v154, v124, v124
	v_fmac_f32_e32 v155, v126, v126
	v_add_f32_e32 v154, v154, v155
	v_mul_f32_e32 v155, v121, v121
	v_fmac_f32_e32 v155, v120, v120
	v_add_f32_e32 v155, v155, v156
	v_add_f32_e32 v154, v154, v155
	v_mul_f32_e32 v155, v113, v113
	v_mul_f32_e32 v156, v115, v115
	v_fmac_f32_e32 v155, v112, v112
	v_fmac_f32_e32 v156, v114, v114
	v_add_f32_e32 v155, v155, v156
	v_add_f32_e32 v154, v154, v155
	s_waitcnt vmcnt(3)
	v_pk_fma_f32 v[90:91], v[90:91], v[130:131], v[170:171]
	v_pk_fma_f32 v[88:89], v[88:89], v[128:129], v[168:169]
	v_mul_f32_e32 v149, v91, v91
	v_mul_f32_e32 v148, v89, v89
	v_fmac_f32_e32 v148, v88, v88
	v_fmac_f32_e32 v149, v90, v90
	v_add_f32_e32 v148, v148, v149
	v_add_f32_e32 v148, v154, v148
	ds_bpermute_b32 v149, v145, v148
	global_store_dwordx4 v[152:153], v[88:91], off offset:528
	s_waitcnt lgkmcnt(0)
	v_add_f32_e32 v148, v148, v149
	ds_bpermute_b32 v149, v147, v148
	s_and_saveexec_b64 s[0:1], vcc
	s_cbranch_execz .LBB0_1032
	v_lshl_add_u32 v150, v146, 4, s39
	s_waitcnt lgkmcnt(0)
	v_add_f32_e32 v148, v148, v149
	ds_write_b32 v150, v148 offset:768
.LBB0_1032:
	s_or_b64 exec, exec, s[0:1]
	v_add_u32_e32 v204, 0x80, v190
	v_ashrrev_i32_e32 v205, 31, v204
	s_waitcnt lgkmcnt(0)
	v_lshlrev_b64 v[148:149], 10, v[204:205]
	v_lshl_add_u64 v[148:149], v[148:149], 0, v[188:189]
	v_lshlrev_b64 v[152:153], 2, v[148:149]
	v_lshl_add_u64 v[154:155], s[62:63], 0, v[152:153]
	global_load_dwordx4 v[148:151], v[154:155], off
	global_load_dwordx4 v[160:163], v[154:155], off offset:16
	global_load_dwordx4 v[164:167], v[154:155], off offset:512
	global_load_dwordx4 v[168:171], v[154:155], off offset:528
	v_lshl_add_u64 v[152:153], s[84:85], 0, v[152:153]
	s_waitcnt vmcnt(3)
	v_pk_fma_f32 v[78:79], v[78:79], v[142:143], v[150:151]
	v_pk_fma_f32 v[76:77], v[76:77], v[140:141], v[148:149]
	global_store_dwordx4 v[152:153], v[76:79], off
	s_waitcnt vmcnt(3)
	v_pk_fma_f32 v[70:71], v[70:71], v[138:139], v[162:163]
	v_pk_fma_f32 v[68:69], v[68:69], v[136:137], v[160:161]
	global_store_dwordx4 v[152:153], v[68:71], off offset:16
	v_mul_f32_e32 v156, v71, v71
	v_fmac_f32_e32 v156, v70, v70
	s_waitcnt vmcnt(3)
	v_pk_fma_f32 v[62:63], v[62:63], v[134:135], v[166:167]
	v_pk_fma_f32 v[60:61], v[60:61], v[132:133], v[164:165]
	global_store_dwordx4 v[152:153], v[60:63], off offset:512
	v_mul_f32_e32 v154, v77, v77
	v_mul_f32_e32 v155, v79, v79
	v_fmac_f32_e32 v154, v76, v76
	v_fmac_f32_e32 v155, v78, v78
	v_add_f32_e32 v154, v154, v155
	v_mul_f32_e32 v155, v69, v69
	v_fmac_f32_e32 v155, v68, v68
	v_add_f32_e32 v155, v155, v156
	v_add_f32_e32 v154, v154, v155
	v_mul_f32_e32 v155, v61, v61
	v_mul_f32_e32 v156, v63, v63
	v_fmac_f32_e32 v155, v60, v60
	v_fmac_f32_e32 v156, v62, v62
	v_add_f32_e32 v155, v155, v156
	v_add_f32_e32 v154, v154, v155
	s_waitcnt vmcnt(3)
	v_pk_fma_f32 v[50:51], v[50:51], v[130:131], v[170:171]
	v_pk_fma_f32 v[48:49], v[48:49], v[128:129], v[168:169]
	v_mul_f32_e32 v149, v51, v51
	v_mul_f32_e32 v148, v49, v49
	v_fmac_f32_e32 v148, v48, v48
	v_fmac_f32_e32 v149, v50, v50
	v_add_f32_e32 v148, v148, v149
	v_add_f32_e32 v148, v154, v148
	ds_bpermute_b32 v149, v145, v148
	global_store_dwordx4 v[152:153], v[48:51], off offset:528
	s_waitcnt lgkmcnt(0)
	v_add_f32_e32 v148, v148, v149
	ds_bpermute_b32 v149, v147, v148
	s_and_saveexec_b64 s[0:1], vcc
	s_cbranch_execz .LBB0_1034
	v_lshl_add_u32 v150, v146, 4, s39
	s_waitcnt lgkmcnt(0)
	v_add_f32_e32 v148, v148, v149
	ds_write_b32 v150, v148 offset:2048
; __device__ __forceinline__ float shfl_idx(float v, int src_lane) { return __builtin_bit_cast(float, __builtin_amdgcn_ds_bpermute(src_lane << 2, __builtin_bit_cast(int, v))); }
;     __device__ __forceinline__ void operator()(f32x4 (&acc)[2][2][4][2], const Unit& u, int wr, int wc, int fr, int fq) const {
;     ...
;             for (int m = 0; m < 4; ++m) { const size_t ro = (size_t)(row0 + ai * HALF + m * 16) * 1024 + col0; float ss = 0.f;
; #pragma unroll
;                 for (int bj = 0; bj < 2; ++bj)
; #pragma unroll
;                     for (int n = 0; n < 2; ++n) { const f32x4 xv = *(const f32x4*)(xin + ro + bj * HALF + 4 * n); const f32x4 x = xv + gv[bj][n] * acc[ai][bj][m][n];
;                         *(f32x4*)(out + ro + bj * HALF + 4 * n) = x; acc[ai][bj][m][n] = x; ss += (x.x * x.x + x.y * x.y) + (x.z * x.z + x.w * x.w); }
;                 if (donorm) { ss += shfl_idx(ss, lane ^ 16); ss += shfl_idx(ss, lane ^ 32); if (fq == 0) lp[(ai * HALF + wr * 64 + m * 16 + fr) * 4 + wc] = ss; }
.LBB0_1034:
	s_or_b64 exec, exec, s[0:1]
	v_add_u32_e32 v206, 0x90, v190
	v_ashrrev_i32_e32 v207, 31, v206
	s_waitcnt lgkmcnt(0)
	v_lshlrev_b64 v[148:149], 10, v[206:207]
	v_lshl_add_u64 v[148:149], v[148:149], 0, v[188:189]
	v_lshlrev_b64 v[152:153], 2, v[148:149]
	v_lshl_add_u64 v[154:155], s[62:63], 0, v[152:153]
	global_load_dwordx4 v[148:151], v[154:155], off
	global_load_dwordx4 v[160:163], v[154:155], off offset:16
	global_load_dwordx4 v[164:167], v[154:155], off offset:512
	global_load_dwordx4 v[168:171], v[154:155], off offset:528
	v_lshl_add_u64 v[152:153], s[84:85], 0, v[152:153]
	s_waitcnt vmcnt(3)
	v_pk_fma_f32 v[46:47], v[46:47], v[142:143], v[150:151]
	v_pk_fma_f32 v[44:45], v[44:45], v[140:141], v[148:149]
	global_store_dwordx4 v[152:153], v[44:47], off
	s_waitcnt vmcnt(3)
	v_pk_fma_f32 v[42:43], v[42:43], v[138:139], v[162:163]
	v_pk_fma_f32 v[40:41], v[40:41], v[136:137], v[160:161]
	global_store_dwordx4 v[152:153], v[40:43], off offset:16
	v_mul_f32_e32 v156, v43, v43
	v_fmac_f32_e32 v156, v42, v42
	s_waitcnt vmcnt(3)
	v_pk_fma_f32 v[38:39], v[38:39], v[134:135], v[166:167]
	v_pk_fma_f32 v[36:37], v[36:37], v[132:133], v[164:165]
	global_store_dwordx4 v[152:153], v[36:39], off offset:512
	v_mul_f32_e32 v154, v45, v45
	v_mul_f32_e32 v155, v47, v47
	v_fmac_f32_e32 v154, v44, v44
	v_fmac_f32_e32 v155, v46, v46
	v_add_f32_e32 v154, v154, v155
	v_mul_f32_e32 v155, v41, v41
	v_fmac_f32_e32 v155, v40, v40
	v_add_f32_e32 v155, v155, v156
	v_add_f32_e32 v154, v154, v155
	v_mul_f32_e32 v155, v37, v37
	v_mul_f32_e32 v156, v39, v39
	v_fmac_f32_e32 v155, v36, v36
	v_fmac_f32_e32 v156, v38, v38
	v_add_f32_e32 v155, v155, v156
	v_add_f32_e32 v154, v154, v155
	s_waitcnt vmcnt(3)
	v_pk_fma_f32 v[34:35], v[34:35], v[130:131], v[170:171]
	v_pk_fma_f32 v[32:33], v[32:33], v[128:129], v[168:169]
	v_mul_f32_e32 v149, v35, v35
	v_mul_f32_e32 v148, v33, v33
	v_fmac_f32_e32 v148, v32, v32
	v_fmac_f32_e32 v149, v34, v34
	v_add_f32_e32 v148, v148, v149
	v_add_f32_e32 v148, v154, v148
	ds_bpermute_b32 v149, v145, v148
	global_store_dwordx4 v[152:153], v[32:35], off offset:528
	s_waitcnt lgkmcnt(0)
	v_add_f32_e32 v148, v148, v149
	ds_bpermute_b32 v149, v147, v148
	s_and_saveexec_b64 s[0:1], vcc
	s_cbranch_execz .LBB0_1036
	v_lshl_add_u32 v150, v146, 4, s39
	s_waitcnt lgkmcnt(0)
	v_add_f32_e32 v148, v148, v149
	ds_write_b32 v150, v148 offset:2304
; __device__ __forceinline__ float shfl_idx(float v, int src_lane) { return __builtin_bit_cast(float, __builtin_amdgcn_ds_bpermute(src_lane << 2, __builtin_bit_cast(int, v))); }
;     __device__ __forceinline__ void operator()(f32x4 (&acc)[2][2][4][2], const Unit& u, int wr, int wc, int fr, int fq) const {
;     ...
;             for (int m = 0; m < 4; ++m) { const size_t ro = (size_t)(row0 + ai * HALF + m * 16) * 1024 + col0; float ss = 0.f;
; #pragma unroll
;                 for (int bj = 0; bj < 2; ++bj)
; #pragma unroll
;                     for (int n = 0; n < 2; ++n) { const f32x4 xv = *(const f32x4*)(xin + ro + bj * HALF + 4 * n); const f32x4 x = xv + gv[bj][n] * acc[ai][bj][m][n];
;                         *(f32x4*)(out + ro + bj * HALF + 4 * n) = x; acc[ai][bj][m][n] = x; ss += (x.x * x.x + x.y * x.y) + (x.z * x.z + x.w * x.w); }
;                 if (donorm) { ss += shfl_idx(ss, lane ^ 16); ss += shfl_idx(ss, lane ^ 32); if (fq == 0) lp[(ai * HALF + wr * 64 + m * 16 + fr) * 4 + wc] = ss; }
.LBB0_1036:
	s_or_b64 exec, exec, s[0:1]
	v_add_u32_e32 v208, 0xa0, v190
	v_ashrrev_i32_e32 v209, 31, v208
	s_waitcnt lgkmcnt(0)
	v_lshlrev_b64 v[148:149], 10, v[208:209]
	v_lshl_add_u64 v[148:149], v[148:149], 0, v[188:189]
	v_lshlrev_b64 v[152:153], 2, v[148:149]
	v_lshl_add_u64 v[154:155], s[62:63], 0, v[152:153]
	global_load_dwordx4 v[148:151], v[154:155], off
	global_load_dwordx4 v[160:163], v[154:155], off offset:16
	global_load_dwordx4 v[164:167], v[154:155], off offset:512
	global_load_dwordx4 v[168:171], v[154:155], off offset:528
	v_lshl_add_u64 v[152:153], s[84:85], 0, v[152:153]
	s_waitcnt vmcnt(3)
	v_pk_fma_f32 v[30:31], v[30:31], v[142:143], v[150:151]
	v_pk_fma_f32 v[28:29], v[28:29], v[140:141], v[148:149]
	global_store_dwordx4 v[152:153], v[28:31], off
	s_waitcnt vmcnt(3)
	v_pk_fma_f32 v[26:27], v[26:27], v[138:139], v[162:163]
	v_pk_fma_f32 v[24:25], v[24:25], v[136:137], v[160:161]
	global_store_dwordx4 v[152:153], v[24:27], off offset:16
	v_mul_f32_e32 v156, v27, v27
	v_fmac_f32_e32 v156, v26, v26
	s_waitcnt vmcnt(3)
	v_pk_fma_f32 v[22:23], v[22:23], v[134:135], v[166:167]
	v_pk_fma_f32 v[20:21], v[20:21], v[132:133], v[164:165]
	global_store_dwordx4 v[152:153], v[20:23], off offset:512
	v_mul_f32_e32 v154, v29, v29
	v_mul_f32_e32 v155, v31, v31
	v_fmac_f32_e32 v154, v28, v28
	v_fmac_f32_e32 v155, v30, v30
	v_add_f32_e32 v154, v154, v155
	v_mul_f32_e32 v155, v25, v25
	v_fmac_f32_e32 v155, v24, v24
	v_add_f32_e32 v155, v155, v156
	v_add_f32_e32 v154, v154, v155
	v_mul_f32_e32 v155, v21, v21
	v_mul_f32_e32 v156, v23, v23
	v_fmac_f32_e32 v155, v20, v20
	v_fmac_f32_e32 v156, v22, v22
	v_add_f32_e32 v155, v155, v156
	v_add_f32_e32 v154, v154, v155
	s_waitcnt vmcnt(3)
	v_pk_fma_f32 v[18:19], v[18:19], v[130:131], v[170:171]
	v_pk_fma_f32 v[16:17], v[16:17], v[128:129], v[168:169]
	v_mul_f32_e32 v149, v19, v19
	v_mul_f32_e32 v148, v17, v17
	v_fmac_f32_e32 v148, v16, v16
	v_fmac_f32_e32 v149, v18, v18
	v_add_f32_e32 v148, v148, v149
	v_add_f32_e32 v148, v154, v148
	ds_bpermute_b32 v149, v145, v148
	global_store_dwordx4 v[152:153], v[16:19], off offset:528
	s_waitcnt lgkmcnt(0)
	v_add_f32_e32 v148, v148, v149
	ds_bpermute_b32 v149, v147, v148
	s_and_saveexec_b64 s[0:1], vcc
	s_cbranch_execz .LBB0_1038
	v_lshl_add_u32 v150, v146, 4, s39
	s_waitcnt lgkmcnt(0)
	v_add_f32_e32 v148, v148, v149
	ds_write_b32 v150, v148 offset:2560
.LBB0_1038:
	s_or_b64 exec, exec, s[0:1]
	v_add_u32_e32 v210, 0xb0, v190
	v_ashrrev_i32_e32 v211, 31, v210
	s_waitcnt lgkmcnt(0)
	v_lshlrev_b64 v[148:149], 10, v[210:211]
	v_lshl_add_u64 v[148:149], v[148:149], 0, v[188:189]
	v_lshlrev_b64 v[152:153], 2, v[148:149]
	v_lshl_add_u64 v[154:155], s[62:63], 0, v[152:153]
	global_load_dwordx4 v[148:151], v[154:155], off
	global_load_dwordx4 v[160:163], v[154:155], off offset:16
	global_load_dwordx4 v[164:167], v[154:155], off offset:512
	global_load_dwordx4 v[168:171], v[154:155], off offset:528
	v_lshl_add_u64 v[152:153], s[84:85], 0, v[152:153]
	s_waitcnt vmcnt(3)
	v_pk_fma_f32 v[14:15], v[14:15], v[142:143], v[150:151]
	v_pk_fma_f32 v[12:13], v[12:13], v[140:141], v[148:149]
	global_store_dwordx4 v[152:153], v[12:15], off
	s_waitcnt vmcnt(3)
	v_pk_fma_f32 v[10:11], v[10:11], v[138:139], v[162:163]
	v_pk_fma_f32 v[8:9], v[8:9], v[136:137], v[160:161]
	global_store_dwordx4 v[152:153], v[8:11], off offset:16
	s_waitcnt vmcnt(3)
	v_pk_fma_f32 v[6:7], v[6:7], v[134:135], v[166:167]
	v_pk_fma_f32 v[4:5], v[4:5], v[132:133], v[164:165]
	global_store_dwordx4 v[152:153], v[4:7], off offset:512
	v_mul_f32_e32 v136, v13, v13
	v_mul_f32_e32 v137, v15, v15
	v_fmac_f32_e32 v136, v12, v12
	v_fmac_f32_e32 v137, v14, v14
	v_add_f32_e32 v136, v136, v137
	v_mul_f32_e32 v137, v9, v9
	v_mul_f32_e32 v138, v11, v11
	v_fmac_f32_e32 v137, v8, v8
	v_fmac_f32_e32 v138, v10, v10
	v_add_f32_e32 v137, v137, v138
	v_add_f32_e32 v136, v136, v137
	v_mul_f32_e32 v137, v5, v5
	v_mul_f32_e32 v138, v7, v7
	v_fmac_f32_e32 v137, v4, v4
	v_fmac_f32_e32 v138, v6, v6
	v_add_f32_e32 v137, v137, v138
	v_add_f32_e32 v136, v136, v137
	s_waitcnt vmcnt(3)
	v_pk_fma_f32 v[2:3], v[2:3], v[130:131], v[170:171]
	v_pk_fma_f32 v[0:1], v[0:1], v[128:129], v[168:169]
	v_mul_f32_e32 v129, v3, v3
	v_mul_f32_e32 v128, v1, v1
	v_fmac_f32_e32 v128, v0, v0
	v_fmac_f32_e32 v129, v2, v2
	v_add_f32_e32 v128, v128, v129
	v_add_f32_e32 v128, v136, v128
	ds_bpermute_b32 v129, v145, v128
	global_store_dwordx4 v[152:153], v[0:3], off offset:528
	s_waitcnt lgkmcnt(0)
	v_add_f32_e32 v128, v128, v129
	ds_bpermute_b32 v129, v147, v128
	s_and_saveexec_b64 s[0:1], vcc
	s_cbranch_execz .LBB0_1040
	v_lshl_add_u32 v130, v146, 4, s39
	s_waitcnt lgkmcnt(0)
	v_add_f32_e32 v128, v128, v129
	ds_write_b32 v130, v128 offset:2816

; __device__ __forceinline__ float shfl_idx(float v, int src_lane) { return __builtin_bit_cast(float, __builtin_amdgcn_ds_bpermute(src_lane << 2, __builtin_bit_cast(int, v))); }
;     __device__ __forceinline__ void operator()(f32x4 (&acc)[2][2][4][2], const Unit& u, int wr, int wc, int fr, int fq) const {
;         const int row0 = u.pm * BM + wr * 64 + fr, col0 = u.pn * BM + wc * 32 + 8 * fq, b = (u.pm * BM) >> 13, lane = fr + 16 * fq, tid = (wr * 4 + wc) * 64 + lane;
;         const float* gp = gate + (size_t)b * 6144 + col0;
;         f32x4 gv[2][2];
; #pragma unroll
;         for (int bj = 0; bj < 2; ++bj)
; #pragma unroll
;             for (int n = 0; n < 2; ++n) gv[bj][n] = *(const f32x4*)(gp + bj * HALF + 4 * n);
; #pragma unroll
;         for (int ai = 0; ai < 2; ++ai)
; #pragma unroll
;             for (int m = 0; m < 4; ++m) { const size_t ro = (size_t)(row0 + ai * HALF + m * 16) * 1024 + col0; float ss = 0.f;
; #pragma unroll
;                 for (int bj = 0; bj < 2; ++bj)
; #pragma unroll
;                     for (int n = 0; n < 2; ++n) { const f32x4 xv = *(const f32x4*)(xin + ro + bj * HALF + 4 * n); const f32x4 x = xv + gv[bj][n] * acc[ai][bj][m][n];
;                         *(f32x4*)(out + ro + bj * HALF + 4 * n) = x; acc[ai][bj][m][n] = x; ss += (x.x * x.x + x.y * x.y) + (x.z * x.z + x.w * x.w); }
;                 if (donorm) { ss += shfl_idx(ss, lane ^ 16); ss += shfl_idx(ss, lane ^ 32); if (fq == 0) lp[(ai * HALF + wr * 64 + m * 16 + fr) * 4 + wc] = ss; }
.LBB0_1072:
	v_and_b32_e32 v168, 63, v199
	v_bfe_u32 v169, v199, 4, 2
	v_lshlrev_b32_e32 v169, 2, v169
	v_xor_b32_e32 v169, v168, v169
	v_and_b32_e32 v170, 0x1c0, v199
	v_add_u32_e32 v173, 64, v170
	v_and_b32_e32 v173, 0x200, v173
	v_lshl_add_u32 v170, v170, 4, v173
	v_bfe_u32 v173, v199, 8, 1
	v_mul_u32_u24_e32 v173, 0x1400, v173
	v_add_u32_e32 v170, v170, v173
	v_add_u32_e32 v170, 0x20000, v170
	v_lshl_add_u32 v174, v169, 4, v170
	v_lshrrev_b32_e32 v171, 2, v168
	v_and_b32_e32 v172, 3, v168
	v_lshlrev_b32_e32 v173, 2, v172
	v_xor_b32_e32 v171, v171, v173
	v_lshl_or_b32 v171, v172, 4, v171
	v_lshl_add_u32 v175, v171, 4, v170
	ds_write_b128 v174, v[0:3]
	ds_read_b128 v[0:3], v175
	ds_write_b128 v174, v[4:7]
	ds_read_b128 v[4:7], v175
	ds_write_b128 v174, v[8:11]
	ds_read_b128 v[8:11], v175
	ds_write_b128 v174, v[12:15]
	ds_read_b128 v[12:15], v175
	ds_write_b128 v174, v[16:19]
	ds_read_b128 v[16:19], v175
	ds_write_b128 v174, v[20:23]
	ds_read_b128 v[20:23], v175
	ds_write_b128 v174, v[24:27]
	ds_read_b128 v[24:27], v175
	ds_write_b128 v174, v[28:31]
	ds_read_b128 v[28:31], v175
	ds_write_b128 v174, v[32:35]
	ds_read_b128 v[32:35], v175
	ds_write_b128 v174, v[36:39]
	ds_read_b128 v[36:39], v175
	ds_write_b128 v174, v[40:43]
	ds_read_b128 v[40:43], v175
	ds_write_b128 v174, v[44:47]
	ds_read_b128 v[44:47], v175
	ds_write_b128 v174, v[48:51]
	ds_read_b128 v[48:51], v175
	ds_write_b128 v174, v[52:55]
	ds_read_b128 v[52:55], v175
	ds_write_b128 v174, v[56:59]
	ds_read_b128 v[56:59], v175
	ds_write_b128 v174, v[60:63]
	ds_read_b128 v[60:63], v175
	ds_write_b128 v174, v[64:67]
	ds_read_b128 v[64:67], v175
	ds_write_b128 v174, v[68:71]
	ds_read_b128 v[68:71], v175
	ds_write_b128 v174, v[72:75]
	ds_read_b128 v[72:75], v175
	ds_write_b128 v174, v[76:79]
	ds_read_b128 v[76:79], v175
	ds_write_b128 v174, v[80:83]
	ds_read_b128 v[80:83], v175
	ds_write_b128 v174, v[84:87]
	ds_read_b128 v[84:87], v175
	ds_write_b128 v174, v[88:91]
	ds_read_b128 v[88:91], v175
	ds_write_b128 v174, v[92:95]
	ds_read_b128 v[92:95], v175
	ds_write_b128 v174, v[96:99]
	ds_read_b128 v[96:99], v175
	ds_write_b128 v174, v[100:103]
	ds_read_b128 v[100:103], v175
	ds_write_b128 v174, v[104:107]
	ds_read_b128 v[104:107], v175
	ds_write_b128 v174, v[108:111]
	ds_read_b128 v[108:111], v175
	ds_write_b128 v174, v[112:115]
	ds_read_b128 v[112:115], v175
	ds_write_b128 v174, v[116:119]
	ds_read_b128 v[116:119], v175
	ds_write_b128 v174, v[120:123]
	ds_read_b128 v[120:123], v175
	ds_write_b128 v174, v[124:127]
	ds_read_b128 v[124:127], v175
	s_waitcnt lgkmcnt(0)
	s_lshl_b32 s0, s16, 8
	v_mov_b32_e32 v154, v199
	s_add_i32 s9, s0, s34
	s_lshl_b32 s0, s18, 8
	s_or_b32 s0, s0, s35
	v_bfe_u32 v214, v154, 2, 4
	v_and_b32_e32 v155, 3, v154
	v_lshl_or_b32 v188, v155, 3, s0
	s_ashr_i32 s0, s16, 5
	v_or_b32_e32 v190, s9, v214
	s_mul_hi_i32 s1, s0, 0x1800
	s_mulk_i32 s0, 0x1800
	v_ashrrev_i32_e32 v191, 31, v190
	s_lshl_b64 s[20:21], s[0:1], 2
	v_readlane_b32 s0, v255, 16
	v_ashrrev_i32_e32 v189, 31, v188
	v_lshlrev_b64 v[128:129], 10, v[190:191]
	s_add_u32 s0, s0, s20
	v_readlane_b32 s1, v255, 17
	v_lshl_add_u64 v[128:129], v[128:129], 0, v[188:189]
	s_addc_u32 s1, s1, s21
	v_lshlrev_b64 v[148:149], 2, v[128:129]
	v_lshl_add_u64 v[132:133], v[188:189], 2, s[0:1]
	v_lshl_add_u64 v[150:151], s[62:63], 0, v[148:149]
	global_load_dwordx4 v[144:147], v[150:151], off
	global_load_dwordx4 v[160:163], v[150:151], off offset:16
	global_load_dwordx4 v[164:167], v[150:151], off offset:512
	global_load_dwordx4 v[168:171], v[150:151], off offset:528
	global_load_dwordx4 v[140:143], v[132:133], off
	global_load_dwordx4 v[136:139], v[132:133], off offset:16
	global_load_dwordx4 v[128:131], v[132:133], off offset:528
	s_nop 0
	global_load_dwordx4 v[132:135], v[132:133], off offset:512
	v_lshl_add_u64 v[152:153], s[84:85], 0, v[148:149]
	v_cmp_eq_u32_e32 vcc, 0, v155
	s_waitcnt vmcnt(0)
	v_pk_fma_f32 v[54:55], v[54:55], v[142:143], v[146:147]
	v_pk_fma_f32 v[52:53], v[52:53], v[140:141], v[144:145]
	global_store_dwordx4 v[152:153], v[52:55], off
	s_waitcnt vmcnt(1)
	v_pk_fma_f32 v[58:59], v[58:59], v[138:139], v[162:163]
	v_pk_fma_f32 v[56:57], v[56:57], v[136:137], v[160:161]
	global_store_dwordx4 v[152:153], v[56:59], off offset:16
	v_mul_f32_e32 v156, v59, v59
	v_fmac_f32_e32 v156, v58, v58
	s_waitcnt vmcnt(2)
	v_pk_fma_f32 v[66:67], v[66:67], v[134:135], v[166:167]
	v_pk_fma_f32 v[64:65], v[64:65], v[132:133], v[164:165]
	global_store_dwordx4 v[152:153], v[64:67], off offset:512
	v_and_b32_e32 v144, 63, v154
	v_mul_f32_e32 v151, v53, v53
	v_mul_f32_e32 v154, v55, v55
	v_fmac_f32_e32 v151, v52, v52
	v_fmac_f32_e32 v154, v54, v54
	v_add_f32_e32 v151, v151, v154
	v_mul_f32_e32 v154, v57, v57
	v_fmac_f32_e32 v154, v56, v56
	v_add_f32_e32 v154, v154, v156
	v_add_f32_e32 v151, v151, v154
	v_mul_f32_e32 v154, v65, v65
	v_mul_f32_e32 v156, v67, v67
	v_fmac_f32_e32 v154, v64, v64
	v_fmac_f32_e32 v156, v66, v66
	v_add_f32_e32 v154, v154, v156
	v_lshlrev_b32_e32 v150, 2, v144
	v_add_f32_e32 v151, v151, v154
	v_xor_b32_e32 v145, 4, v150
	s_waitcnt vmcnt(3)
	v_pk_fma_f32 v[74:75], v[74:75], v[130:131], v[170:171]
	v_pk_fma_f32 v[72:73], v[72:73], v[128:129], v[168:169]
	v_mul_f32_e32 v147, v75, v75
	v_mul_f32_e32 v146, v73, v73
	v_fmac_f32_e32 v146, v72, v72
	v_fmac_f32_e32 v147, v74, v74
	v_add_f32_e32 v146, v146, v147
	v_add_f32_e32 v146, v151, v146
	ds_bpermute_b32 v148, v145, v146
	v_xor_b32_e32 v147, 8, v150
	global_store_dwordx4 v[152:153], v[72:75], off offset:528
	s_waitcnt lgkmcnt(0)
	v_add_f32_e32 v148, v146, v148
	ds_bpermute_b32 v149, v147, v148
	v_or_b32_e32 v146, s34, v214
	s_and_saveexec_b64 s[0:1], vcc
	s_cbranch_execz .LBB0_1074
	v_lshl_add_u32 v150, v146, 4, s39
	s_waitcnt lgkmcnt(0)
	v_add_f32_e32 v148, v148, v149
	ds_write_b32 v150, v148
